# GEMM tiles: first K-loop trip peeled with C = 0 MFMAs; per-tile zeroing of 128 accumulator registers removed (4 GEMM phase types)
# speedup vs baseline: 1.0042x; 1.0042x over previous
; #define PG8_STAGE(bufoff, gbase, voff) do { _Pragma("unroll") for (int _i = 0; _i < 2; ++_i) \
;         __builtin_amdgcn_global_load_lds((const unsigned*)((const char*)(gbase) + (voff)[_i]), (LAS unsigned*)(lds + (bufoff) + ldsw + _i * 8192), 16, 0, 0); } while (0)
; #define PG8_LDA(dst, b, h) do { _Pragma("unroll") for (int m = 0; m < 4; ++m) _Pragma("unroll") for (int k = 0; k < 2; ++k) dst[m][k] = *(const LAS bf16x8*)(lds + PG8_SA(b, h) + aoff + m * 2048 + k * 1024); } while (0)
; #define PG8_LDB(dst, b, h) do { _Pragma("unroll") for (int n = 0; n < 2; ++n) _Pragma("unroll") for (int k = 0; k < 2; ++k) dst[n][k] = *(const LAS bf16x8*)(lds + PG8_SB(b, h) + boff + n * 2048 + k * 1024); } while (0)
; #define PG8_MMA(ai, bj, At, Bt) do { __builtin_amdgcn_s_setprio(1); _Pragma("unroll") for (int m = 0; m < 4; ++m) _Pragma("unroll") for (int n = 0; n < 2; ++n) _Pragma("unroll") for (int k = 0; k < 2; ++k) \
;         acc[ai][bj][m][n] = __builtin_amdgcn_mfma_f32_16x16x32_bf16(Bt[n][k], At[m][k], acc[ai][bj][m][n], 0, 0, 0); __builtin_amdgcn_s_setprio(0); } while (0)
; #define PG8_BAR __builtin_amdgcn_s_barrier()
; template <class Epi, bool SEG>
; __device__ __forceinline__ void gemm_phase(LAS unsigned char* lds, const Gemm g, const int G, const int cidx, const Epi& E) {
;     ...
;         const bool has_next = S.next(ui + 1, nxt);
;         const char* nA = has_next ? (const char*)g.A + (long)nxt.pm * (long)tstepA + aoff0 : cA; const char* nB = has_next ? (const char*)g.Bt + (size_t)nxt.pn * tstepB : cB;
;         for (int t = 0; t < nt; t += 2) {
;             const bool last = (t == nt - 2);
;             const char* a1 = cA + (size_t)(t + 1) * kstep;
;             const char* a2 = last ? nA : cA + (size_t)(t + 2) * kstep; const char* b2 = last ? nB : cB + (size_t)(t + 2) * kstep;
;             const char* a3 = a2 + kstep; const char* b3 = b2 + kstep;
;             PG8_LDB(B0, 0, 0); PG8_LDB(B1, 0, 1); PG8_SCHED; PG8_LDA(At, 0, 0); PG8_STAGE(PG8_SA(1, 1), a1 + hstepA, voffA);
;             PG8_WAIT_V(8); PG8_WAIT_L(0); PG8_BAR; PG8_MMA(0, 0, At, B0); PG8_MMA(0, 1, At, B1); PG8_BAR; PG8_SCHED;
;             PG8_LDA(At, 0, 1); PG8_STAGE(PG8_SB(0, 0), b2, voffB); PG8_STAGE(PG8_SB(0, 1), b2 + hstepB, voffB); PG8_STAGE(PG8_SA(0, 0), a2, voffA);
;             PG8_WAIT_V(8); PG8_WAIT_L(0); PG8_BAR; PG8_MMA(1, 0, At, B0); PG8_MMA(1, 1, At, B1); PG8_BAR; PG8_SCHED;
.LBB0_293:
	s_ashr_i32 s23, s22, 31
	s_lshl_b64 s[42:43], s[22:23], 19
	s_add_u32 s42, s82, s42
	s_addc_u32 s43, s83, s43
	s_and_b64 s[44:45], s[40:41], exec
	s_cselect_b32 s7, s43, s47
	s_cselect_b32 s23, s42, s46
	s_ashr_i32 s21, s20, 31
	s_lshl_b64 s[44:45], s[20:21], 19
	s_add_u32 s44, s12, s44
	s_addc_u32 s45, s13, s45
	s_and_b64 s[50:51], s[40:41], exec
	s_cselect_b32 s21, s45, s49
	s_cselect_b32 s59, s44, s48
	s_add_u32 s46, s46, 0x40080
	s_addc_u32 s47, s47, 0
	s_add_u32 s60, s48, 0x100
	s_addc_u32 s61, s49, 0
	s_mov_b32 s62, -2
	s_add_u32 s48, s46, 0xfffc0080
	s_addc_u32 s49, s47, -1
	s_add_i32 s63, 0, 0x10000
	s_cmp_eq_u32 s62, 12
	s_cselect_b32 s51, s7, s49
	s_cselect_b32 s50, s23, s48
	s_cselect_b32 s49, s21, s61
	s_cselect_b32 s48, s59, s60
	s_add_i32 s66, 0, 0x14000
	v_add_u32_e32 v146, s63, v175
	v_add_u32_e32 v170, s66, v175
	ds_read_b128 v[134:137], v146
	ds_read_b128 v[138:141], v146 offset:1024
	ds_read_b128 v[142:145], v146 offset:2048
	ds_read_b128 v[146:149], v146 offset:3072
	ds_read_b128 v[158:161], v170
	ds_read_b128 v[162:165], v170 offset:1024
	ds_read_b128 v[166:169], v170 offset:2048
	ds_read_b128 v[170:173], v170 offset:3072
	v_lshl_add_u64 v[200:201], s[46:47], 0, v[154:155]
	s_add_i32 m0, s39, 0xc000
	ds_read_b128 v[180:183], v179
	ds_read_b128 v[184:187], v179 offset:1024
	ds_read_b128 v[188:191], v179 offset:2048
	ds_read_b128 v[192:195], v179 offset:3072
	ds_read_b128 v[196:199], v179 offset:4096
	ds_read_b128 v[212:215], v179 offset:5120
	ds_read_b128 v[216:219], v179 offset:6144
	ds_read_b128 v[220:223], v179 offset:7168
	global_load_lds_dwordx4 v[200:201], off
	v_lshl_add_u64 v[200:201], s[46:47], 0, v[156:157]
	s_add_i32 m0, s39, 0xe000
	s_nop 0
	global_load_lds_dwordx4 v[200:201], off
	s_waitcnt vmcnt(8)
	s_waitcnt lgkmcnt(0)
	s_setprio 1
	s_barrier
	v_mfma_f32_16x16x32_bf16 v[130:133], v[134:137], v[180:183], 0
	v_mfma_f32_16x16x32_bf16 v[126:129], v[142:145], v[180:183], 0
	v_mfma_f32_16x16x32_bf16 v[118:121], v[134:137], v[188:191], 0
	v_mfma_f32_16x16x32_bf16 v[110:113], v[142:145], v[188:191], 0
	v_mfma_f32_16x16x32_bf16 v[102:105], v[134:137], v[196:199], 0
	v_mfma_f32_16x16x32_bf16 v[94:97], v[142:145], v[196:199], 0
	v_mfma_f32_16x16x32_bf16 v[86:89], v[134:137], v[216:219], 0
	v_mfma_f32_16x16x32_bf16 v[78:81], v[142:145], v[216:219], 0
	v_mfma_f32_16x16x32_bf16 v[130:133], v[138:141], v[184:187], v[130:133]
	v_mfma_f32_16x16x32_bf16 v[126:129], v[146:149], v[184:187], v[126:129]
	v_mfma_f32_16x16x32_bf16 v[118:121], v[138:141], v[192:195], v[118:121]
	v_mfma_f32_16x16x32_bf16 v[110:113], v[146:149], v[192:195], v[110:113]
	v_mfma_f32_16x16x32_bf16 v[102:105], v[138:141], v[212:215], v[102:105]
	v_mfma_f32_16x16x32_bf16 v[94:97], v[146:149], v[212:215], v[94:97]
	v_mfma_f32_16x16x32_bf16 v[86:89], v[138:141], v[220:223], v[86:89]
	v_mfma_f32_16x16x32_bf16 v[78:81], v[146:149], v[220:223], v[78:81]
	s_setprio 0
	s_setprio 1
	v_mfma_f32_16x16x32_bf16 v[122:125], v[158:161], v[180:183], 0
	v_mfma_f32_16x16x32_bf16 v[114:117], v[166:169], v[180:183], 0
	v_mfma_f32_16x16x32_bf16 v[106:109], v[158:161], v[188:191], 0
	v_mfma_f32_16x16x32_bf16 v[98:101], v[166:169], v[188:191], 0
	v_mfma_f32_16x16x32_bf16 v[90:93], v[158:161], v[196:199], 0
	v_mfma_f32_16x16x32_bf16 v[82:85], v[166:169], v[196:199], 0
	v_mfma_f32_16x16x32_bf16 v[74:77], v[158:161], v[216:219], 0
	v_mfma_f32_16x16x32_bf16 v[70:73], v[166:169], v[216:219], 0
	v_mfma_f32_16x16x32_bf16 v[122:125], v[162:165], v[184:187], v[122:125]
	v_mfma_f32_16x16x32_bf16 v[114:117], v[170:173], v[184:187], v[114:117]
	v_mfma_f32_16x16x32_bf16 v[106:109], v[162:165], v[192:195], v[106:109]
	v_mfma_f32_16x16x32_bf16 v[98:101], v[170:173], v[192:195], v[98:101]
	v_mfma_f32_16x16x32_bf16 v[90:93], v[162:165], v[212:215], v[90:93]
	v_mfma_f32_16x16x32_bf16 v[82:85], v[170:173], v[212:215], v[82:85]
	v_mfma_f32_16x16x32_bf16 v[74:77], v[162:165], v[220:223], v[74:77]
	v_mfma_f32_16x16x32_bf16 v[70:73], v[170:173], v[220:223], v[70:73]
	s_barrier
	s_setprio 0
	s_add_i32 s63, s63, s1
	v_lshl_add_u64 v[200:201], s[48:49], 0, v[0:1]
	s_mov_b32 m0, s63
	ds_read_b128 v[180:183], v179 offset:16384
	ds_read_b128 v[184:187], v179 offset:17408
	ds_read_b128 v[188:191], v179 offset:18432
	ds_read_b128 v[192:195], v179 offset:19456
	ds_read_b128 v[196:199], v179 offset:20480
	ds_read_b128 v[212:215], v179 offset:21504
	ds_read_b128 v[216:219], v179 offset:22528
	ds_read_b128 v[220:223], v179 offset:23552
	global_load_lds_dwordx4 v[200:201], off
	s_add_i32 m0, s63, 0x2000
	s_add_u32 s64, s48, 0x40000
	v_lshl_add_u64 v[224:225], s[48:49], 0, v[14:15]
	s_addc_u32 s65, s49, 0
	s_add_i32 s63, s66, s1
	global_load_lds_dwordx4 v[224:225], off
	v_lshl_add_u64 v[226:227], s[64:65], 0, v[0:1]
	s_mov_b32 m0, s63
	v_lshl_add_u64 v[228:229], s[50:51], 0, v[150:151]
	global_load_lds_dwordx4 v[226:227], off
	v_lshl_add_u64 v[226:227], s[64:65], 0, v[14:15]
	s_add_i32 m0, s63, 0x2000
	s_nop 0
	global_load_lds_dwordx4 v[226:227], off
	v_lshl_add_u64 v[226:227], s[50:51], 0, v[152:153]
	s_mov_b32 m0, s39
	s_nop 0
	global_load_lds_dwordx4 v[226:227], off
	s_mov_b32 m0, s52
	s_nop 0
	global_load_lds_dwordx4 v[228:229], off
	s_waitcnt vmcnt(8)
	s_waitcnt lgkmcnt(0)
	s_setprio 1
	s_barrier
; #define PG8_STAGE(bufoff, gbase, voff) do { _Pragma("unroll") for (int _i = 0; _i < 2; ++_i) \
;         __builtin_amdgcn_global_load_lds((const unsigned*)((const char*)(gbase) + (voff)[_i]), (LAS unsigned*)(lds + (bufoff) + ldsw + _i * 8192), 16, 0, 0); } while (0)
; #define PG8_LDA(dst, b, h) do { _Pragma("unroll") for (int m = 0; m < 4; ++m) _Pragma("unroll") for (int k = 0; k < 2; ++k) dst[m][k] = *(const LAS bf16x8*)(lds + PG8_SA(b, h) + aoff + m * 2048 + k * 1024); } while (0)
; #define PG8_LDB(dst, b, h) do { _Pragma("unroll") for (int n = 0; n < 2; ++n) _Pragma("unroll") for (int k = 0; k < 2; ++k) dst[n][k] = *(const LAS bf16x8*)(lds + PG8_SB(b, h) + boff + n * 2048 + k * 1024); } while (0)
; #define PG8_MMA(ai, bj, At, Bt) do { __builtin_amdgcn_s_setprio(1); _Pragma("unroll") for (int m = 0; m < 4; ++m) _Pragma("unroll") for (int n = 0; n < 2; ++n) _Pragma("unroll") for (int k = 0; k < 2; ++k) \
;         acc[ai][bj][m][n] = __builtin_amdgcn_mfma_f32_16x16x32_bf16(Bt[n][k], At[m][k], acc[ai][bj][m][n], 0, 0, 0); __builtin_amdgcn_s_setprio(0); } while (0)
; #define PG8_WAIT_V(n) asm volatile("s_waitcnt vmcnt(" #n ")" ::: "memory")
; #define PG8_WAIT_L(n) asm volatile("s_waitcnt lgkmcnt(" #n ")" ::: "memory")
; #define PG8_BAR __builtin_amdgcn_s_barrier()
; #define PG8_SCHED __builtin_amdgcn_sched_barrier(0)
; template <class Epi, bool SEG>
; __device__ __forceinline__ void gemm_phase(LAS unsigned char* lds, const Gemm g, const int G, const int cidx, const Epi& E) {
;     ...
;             PG8_WAIT_V(8); PG8_WAIT_L(0); PG8_BAR; PG8_MMA(1, 0, At, B0); PG8_MMA(1, 1, At, B1); PG8_BAR; PG8_SCHED;
;             PG8_LDB(B0, 1, 0); PG8_LDB(B1, 1, 1); PG8_SCHED; PG8_LDA(At, 1, 0); PG8_STAGE(PG8_SA(0, 1), a2 + hstepA, voffA);
;             PG8_WAIT_V(8); PG8_WAIT_L(0); PG8_BAR; PG8_MMA(0, 0, At, B0); PG8_MMA(0, 1, At, B1); PG8_BAR; PG8_SCHED;
;             PG8_LDA(At, 1, 1); PG8_STAGE(PG8_SB(1, 0), b3, voffB); PG8_STAGE(PG8_SB(1, 1), b3 + hstepB, voffB); PG8_STAGE(PG8_SA(1, 0), a3, voffA);
	v_mfma_f32_16x16x32_bf16 v[66:69], v[134:137], v[180:183], 0
	v_mfma_f32_16x16x32_bf16 v[62:65], v[142:145], v[180:183], 0
	v_mfma_f32_16x16x32_bf16 v[54:57], v[134:137], v[188:191], 0
	v_mfma_f32_16x16x32_bf16 v[46:49], v[142:145], v[188:191], 0
	v_mfma_f32_16x16x32_bf16 v[38:41], v[134:137], v[196:199], 0
	v_mfma_f32_16x16x32_bf16 v[30:33], v[142:145], v[196:199], 0
	v_mfma_f32_16x16x32_bf16 v[22:25], v[134:137], v[216:219], 0
	v_mfma_f32_16x16x32_bf16 v[10:13], v[142:145], v[216:219], 0
	v_mfma_f32_16x16x32_bf16 v[66:69], v[138:141], v[184:187], v[66:69]
	v_mfma_f32_16x16x32_bf16 v[62:65], v[146:149], v[184:187], v[62:65]
	v_mfma_f32_16x16x32_bf16 v[54:57], v[138:141], v[192:195], v[54:57]
	v_mfma_f32_16x16x32_bf16 v[46:49], v[146:149], v[192:195], v[46:49]
	v_mfma_f32_16x16x32_bf16 v[38:41], v[138:141], v[212:215], v[38:41]
	v_mfma_f32_16x16x32_bf16 v[30:33], v[146:149], v[212:215], v[30:33]
	v_mfma_f32_16x16x32_bf16 v[22:25], v[138:141], v[220:223], v[22:25]
	v_mfma_f32_16x16x32_bf16 v[10:13], v[146:149], v[220:223], v[10:13]
	s_setprio 0
	s_setprio 1
	v_mfma_f32_16x16x32_bf16 v[58:61], v[158:161], v[180:183], 0
	v_mfma_f32_16x16x32_bf16 v[50:53], v[166:169], v[180:183], 0
	v_mfma_f32_16x16x32_bf16 v[42:45], v[158:161], v[188:191], 0
	v_mfma_f32_16x16x32_bf16 v[34:37], v[166:169], v[188:191], 0
	v_mfma_f32_16x16x32_bf16 v[26:29], v[158:161], v[196:199], 0
	v_mfma_f32_16x16x32_bf16 v[18:21], v[166:169], v[196:199], 0
	v_mfma_f32_16x16x32_bf16 v[6:9], v[158:161], v[216:219], 0
	v_mfma_f32_16x16x32_bf16 v[2:5], v[166:169], v[216:219], 0
	v_mfma_f32_16x16x32_bf16 v[58:61], v[162:165], v[184:187], v[58:61]
	v_mfma_f32_16x16x32_bf16 v[50:53], v[170:173], v[184:187], v[50:53]
	v_mfma_f32_16x16x32_bf16 v[42:45], v[162:165], v[192:195], v[42:45]
	v_mfma_f32_16x16x32_bf16 v[34:37], v[170:173], v[192:195], v[34:37]
	v_mfma_f32_16x16x32_bf16 v[26:29], v[162:165], v[212:215], v[26:29]
	v_mfma_f32_16x16x32_bf16 v[18:21], v[170:173], v[212:215], v[18:21]
	v_mfma_f32_16x16x32_bf16 v[6:9], v[162:165], v[220:223], v[6:9]
	v_mfma_f32_16x16x32_bf16 v[2:5], v[170:173], v[220:223], v[2:5]
	s_barrier
	s_setprio 0
	s_add_i32 s63, 0, 0x18000
	s_add_i32 s64, 0, 0x1c000
	v_add_u32_e32 v146, s63, v175
	v_add_u32_e32 v170, s64, v175
	ds_read_b128 v[134:137], v146
	ds_read_b128 v[138:141], v146 offset:1024
	ds_read_b128 v[142:145], v146 offset:2048
	ds_read_b128 v[146:149], v146 offset:3072
	ds_read_b128 v[158:161], v170
	ds_read_b128 v[162:165], v170 offset:1024
	ds_read_b128 v[166:169], v170 offset:2048
	ds_read_b128 v[170:173], v170 offset:3072
	s_add_u32 s50, s50, 0x40000
	s_addc_u32 s51, s51, 0
	s_mov_b32 m0, s53
	v_lshl_add_u64 v[244:245], s[50:51], 0, v[152:153]
	ds_read_b128 v[180:183], v179 offset:32768
	ds_read_b128 v[184:187], v179 offset:33792
	ds_read_b128 v[188:191], v179 offset:34816
	ds_read_b128 v[192:195], v179 offset:35840
	ds_read_b128 v[196:199], v179 offset:36864
	ds_read_b128 v[212:215], v179 offset:37888
	ds_read_b128 v[216:219], v179 offset:38912
	ds_read_b128 v[220:223], v179 offset:39936
	global_load_lds_dwordx4 v[244:245], off
	v_lshl_add_u64 v[244:245], s[50:51], 0, v[150:151]
	s_mov_b32 m0, s54
	s_nop 0
	global_load_lds_dwordx4 v[244:245], off
	s_waitcnt vmcnt(8)
	s_waitcnt lgkmcnt(0)
	s_setprio 1
	s_barrier
	v_mfma_f32_16x16x32_bf16 v[130:133], v[134:137], v[180:183], v[130:133]
	v_mfma_f32_16x16x32_bf16 v[126:129], v[142:145], v[180:183], v[126:129]
	v_mfma_f32_16x16x32_bf16 v[118:121], v[134:137], v[188:191], v[118:121]
	v_mfma_f32_16x16x32_bf16 v[110:113], v[142:145], v[188:191], v[110:113]
	v_mfma_f32_16x16x32_bf16 v[102:105], v[134:137], v[196:199], v[102:105]
	v_mfma_f32_16x16x32_bf16 v[94:97], v[142:145], v[196:199], v[94:97]
	v_mfma_f32_16x16x32_bf16 v[86:89], v[134:137], v[216:219], v[86:89]
	v_mfma_f32_16x16x32_bf16 v[78:81], v[142:145], v[216:219], v[78:81]
	v_mfma_f32_16x16x32_bf16 v[130:133], v[138:141], v[184:187], v[130:133]
	v_mfma_f32_16x16x32_bf16 v[126:129], v[146:149], v[184:187], v[126:129]
	v_mfma_f32_16x16x32_bf16 v[118:121], v[138:141], v[192:195], v[118:121]
	v_mfma_f32_16x16x32_bf16 v[110:113], v[146:149], v[192:195], v[110:113]
	v_mfma_f32_16x16x32_bf16 v[102:105], v[138:141], v[212:215], v[102:105]
	v_mfma_f32_16x16x32_bf16 v[94:97], v[146:149], v[212:215], v[94:97]
	v_mfma_f32_16x16x32_bf16 v[86:89], v[138:141], v[220:223], v[86:89]
	v_mfma_f32_16x16x32_bf16 v[78:81], v[146:149], v[220:223], v[78:81]
	s_setprio 0
	s_setprio 1
	v_mfma_f32_16x16x32_bf16 v[122:125], v[158:161], v[180:183], v[122:125]
	v_mfma_f32_16x16x32_bf16 v[114:117], v[166:169], v[180:183], v[114:117]
	v_mfma_f32_16x16x32_bf16 v[106:109], v[158:161], v[188:191], v[106:109]
	v_mfma_f32_16x16x32_bf16 v[98:101], v[166:169], v[188:191], v[98:101]
	v_mfma_f32_16x16x32_bf16 v[90:93], v[158:161], v[196:199], v[90:93]
	v_mfma_f32_16x16x32_bf16 v[82:85], v[166:169], v[196:199], v[82:85]
	v_mfma_f32_16x16x32_bf16 v[74:77], v[158:161], v[216:219], v[74:77]
	v_mfma_f32_16x16x32_bf16 v[70:73], v[166:169], v[216:219], v[70:73]
	v_mfma_f32_16x16x32_bf16 v[122:125], v[162:165], v[184:187], v[122:125]
	v_mfma_f32_16x16x32_bf16 v[114:117], v[170:173], v[184:187], v[114:117]
	v_mfma_f32_16x16x32_bf16 v[106:109], v[162:165], v[192:195], v[106:109]
	v_mfma_f32_16x16x32_bf16 v[98:101], v[170:173], v[192:195], v[98:101]
	v_mfma_f32_16x16x32_bf16 v[90:93], v[162:165], v[212:215], v[90:93]
	v_mfma_f32_16x16x32_bf16 v[82:85], v[170:173], v[212:215], v[82:85]
	v_mfma_f32_16x16x32_bf16 v[74:77], v[162:165], v[220:223], v[74:77]
	v_mfma_f32_16x16x32_bf16 v[70:73], v[170:173], v[220:223], v[70:73]
	s_barrier
; #define PG8_STAGE(bufoff, gbase, voff) do { _Pragma("unroll") for (int _i = 0; _i < 2; ++_i) \
;         __builtin_amdgcn_global_load_lds((const unsigned*)((const char*)(gbase) + (voff)[_i]), (LAS unsigned*)(lds + (bufoff) + ldsw + _i * 8192), 16, 0, 0); } while (0)
; #define PG8_LDA(dst, b, h) do { _Pragma("unroll") for (int m = 0; m < 4; ++m) _Pragma("unroll") for (int k = 0; k < 2; ++k) dst[m][k] = *(const LAS bf16x8*)(lds + PG8_SA(b, h) + aoff + m * 2048 + k * 1024); } while (0)
; #define PG8_MMA(ai, bj, At, Bt) do { __builtin_amdgcn_s_setprio(1); _Pragma("unroll") for (int m = 0; m < 4; ++m) _Pragma("unroll") for (int n = 0; n < 2; ++n) _Pragma("unroll") for (int k = 0; k < 2; ++k) \
;         acc[ai][bj][m][n] = __builtin_amdgcn_mfma_f32_16x16x32_bf16(Bt[n][k], At[m][k], acc[ai][bj][m][n], 0, 0, 0); __builtin_amdgcn_s_setprio(0); } while (0)
; #define PG8_WAIT_V(n) asm volatile("s_waitcnt vmcnt(" #n ")" ::: "memory")
; #define PG8_WAIT_L(n) asm volatile("s_waitcnt lgkmcnt(" #n ")" ::: "memory")
; #define PG8_BAR __builtin_amdgcn_s_barrier()
; #define PG8_SCHED __builtin_amdgcn_sched_barrier(0)
; template <class Epi, bool SEG>
; __device__ __forceinline__ void gemm_phase(LAS unsigned char* lds, const Gemm g, const int G, const int cidx, const Epi& E) {
;     ...
;             PG8_LDA(At, 1, 1); PG8_STAGE(PG8_SB(1, 0), b3, voffB); PG8_STAGE(PG8_SB(1, 1), b3 + hstepB, voffB); PG8_STAGE(PG8_SA(1, 0), a3, voffA);
;             PG8_WAIT_V(8); PG8_WAIT_L(0); PG8_BAR; PG8_MMA(1, 0, At, B0); PG8_MMA(1, 1, At, B1); PG8_BAR; PG8_SCHED;
;         }
	s_setprio 0
	s_add_i32 s50, s63, s1
	v_lshl_add_u64 v[200:201], v[200:201], 0, s[28:29]
	s_mov_b32 m0, s50
	ds_read_b128 v[180:183], v179 offset:49152
	ds_read_b128 v[184:187], v179 offset:50176
	ds_read_b128 v[188:191], v179 offset:51200
	ds_read_b128 v[192:195], v179 offset:52224
	ds_read_b128 v[196:199], v179 offset:53248
	ds_read_b128 v[212:215], v179 offset:54272
	ds_read_b128 v[216:219], v179 offset:55296
	ds_read_b128 v[220:223], v179 offset:56320
	global_load_lds_dwordx4 v[200:201], off
	s_add_i32 m0, s50, 0x2000
	s_add_u32 s48, s48, 0x40080
	v_lshl_add_u64 v[200:201], v[224:225], 0, s[28:29]
	s_addc_u32 s49, s49, 0
	s_add_i32 s50, s64, s1
	global_load_lds_dwordx4 v[200:201], off
	v_lshl_add_u64 v[200:201], s[48:49], 0, v[0:1]
	s_mov_b32 m0, s50
	s_nop 0
	global_load_lds_dwordx4 v[200:201], off
	v_lshl_add_u64 v[200:201], s[48:49], 0, v[14:15]
	s_add_i32 m0, s50, 0x2000
	s_nop 0
	global_load_lds_dwordx4 v[200:201], off
	v_lshl_add_u64 v[200:201], v[226:227], 0, s[28:29]
	s_mov_b32 m0, s55
	s_nop 0
	global_load_lds_dwordx4 v[200:201], off
	v_lshl_add_u64 v[200:201], v[228:229], 0, s[28:29]
	s_mov_b32 m0, s56
	s_nop 0
	global_load_lds_dwordx4 v[200:201], off
	s_waitcnt vmcnt(8)
	s_waitcnt lgkmcnt(0)
	s_setprio 1
	s_barrier
	v_mfma_f32_16x16x32_bf16 v[66:69], v[134:137], v[180:183], v[66:69]
	v_mfma_f32_16x16x32_bf16 v[62:65], v[142:145], v[180:183], v[62:65]
	v_mfma_f32_16x16x32_bf16 v[54:57], v[134:137], v[188:191], v[54:57]
	v_mfma_f32_16x16x32_bf16 v[46:49], v[142:145], v[188:191], v[46:49]
	v_mfma_f32_16x16x32_bf16 v[38:41], v[134:137], v[196:199], v[38:41]
	v_mfma_f32_16x16x32_bf16 v[30:33], v[142:145], v[196:199], v[30:33]
	v_mfma_f32_16x16x32_bf16 v[22:25], v[134:137], v[216:219], v[22:25]
	v_mfma_f32_16x16x32_bf16 v[10:13], v[142:145], v[216:219], v[10:13]
	v_mfma_f32_16x16x32_bf16 v[66:69], v[138:141], v[184:187], v[66:69]
	v_mfma_f32_16x16x32_bf16 v[62:65], v[146:149], v[184:187], v[62:65]
	v_mfma_f32_16x16x32_bf16 v[54:57], v[138:141], v[192:195], v[54:57]
	v_mfma_f32_16x16x32_bf16 v[46:49], v[146:149], v[192:195], v[46:49]
	v_mfma_f32_16x16x32_bf16 v[38:41], v[138:141], v[212:215], v[38:41]
	v_mfma_f32_16x16x32_bf16 v[30:33], v[146:149], v[212:215], v[30:33]
	v_mfma_f32_16x16x32_bf16 v[22:25], v[138:141], v[220:223], v[22:25]
	v_mfma_f32_16x16x32_bf16 v[10:13], v[146:149], v[220:223], v[10:13]
	s_setprio 0
	s_setprio 1
	v_mfma_f32_16x16x32_bf16 v[58:61], v[158:161], v[180:183], v[58:61]
	v_mfma_f32_16x16x32_bf16 v[50:53], v[166:169], v[180:183], v[50:53]
	v_mfma_f32_16x16x32_bf16 v[42:45], v[158:161], v[188:191], v[42:45]
	v_mfma_f32_16x16x32_bf16 v[34:37], v[166:169], v[188:191], v[34:37]
	v_mfma_f32_16x16x32_bf16 v[26:29], v[158:161], v[196:199], v[26:29]
	v_mfma_f32_16x16x32_bf16 v[18:21], v[166:169], v[196:199], v[18:21]
	v_mfma_f32_16x16x32_bf16 v[6:9], v[158:161], v[216:219], v[6:9]
	v_mfma_f32_16x16x32_bf16 v[2:5], v[166:169], v[216:219], v[2:5]
	v_mfma_f32_16x16x32_bf16 v[58:61], v[162:165], v[184:187], v[58:61]
	v_mfma_f32_16x16x32_bf16 v[50:53], v[170:173], v[184:187], v[50:53]
	v_mfma_f32_16x16x32_bf16 v[42:45], v[162:165], v[192:195], v[42:45]
	v_mfma_f32_16x16x32_bf16 v[34:37], v[170:173], v[192:195], v[34:37]
	v_mfma_f32_16x16x32_bf16 v[26:29], v[162:165], v[212:215], v[26:29]
	v_mfma_f32_16x16x32_bf16 v[18:21], v[170:173], v[212:215], v[18:21]
	v_mfma_f32_16x16x32_bf16 v[6:9], v[162:165], v[220:223], v[6:9]
	v_mfma_f32_16x16x32_bf16 v[2:5], v[170:173], v[220:223], v[2:5]
	s_barrier
	s_setprio 0
	s_add_i32 s62, s62, 2
	s_add_u32 s46, s46, 0x100
	s_addc_u32 s47, s47, 0
	s_add_u32 s60, s60, 0x100
	s_addc_u32 s61, s61, 0

; #define PG8_STAGE(bufoff, gbase, voff) do { _Pragma("unroll") for (int _i = 0; _i < 2; ++_i) \
;         __builtin_amdgcn_global_load_lds((const unsigned*)((const char*)(gbase) + (voff)[_i]), (LAS unsigned*)(lds + (bufoff) + ldsw + _i * 8192), 16, 0, 0); } while (0)
; #define PG8_LDA(dst, b, h) do { _Pragma("unroll") for (int m = 0; m < 4; ++m) _Pragma("unroll") for (int k = 0; k < 2; ++k) dst[m][k] = *(const LAS bf16x8*)(lds + PG8_SA(b, h) + aoff + m * 2048 + k * 1024); } while (0)
; #define PG8_LDB(dst, b, h) do { _Pragma("unroll") for (int n = 0; n < 2; ++n) _Pragma("unroll") for (int k = 0; k < 2; ++k) dst[n][k] = *(const LAS bf16x8*)(lds + PG8_SB(b, h) + boff + n * 2048 + k * 1024); } while (0)
; #define PG8_MMA(ai, bj, At, Bt) do { __builtin_amdgcn_s_setprio(1); _Pragma("unroll") for (int m = 0; m < 4; ++m) _Pragma("unroll") for (int n = 0; n < 2; ++n) _Pragma("unroll") for (int k = 0; k < 2; ++k) \
;         acc[ai][bj][m][n] = __builtin_amdgcn_mfma_f32_16x16x32_bf16(Bt[n][k], At[m][k], acc[ai][bj][m][n], 0, 0, 0); __builtin_amdgcn_s_setprio(0); } while (0)
; #define PG8_BAR __builtin_amdgcn_s_barrier()
; template <class Epi, bool SEG>
; __device__ __forceinline__ void gemm_phase(LAS unsigned char* lds, const Gemm g, const int G, const int cidx, const Epi& E) {
;     ...
;         const bool has_next = S.next(ui + 1, nxt);
;         const char* nA = has_next ? (const char*)g.A + (long)nxt.pm * (long)tstepA + aoff0 : cA; const char* nB = has_next ? (const char*)g.Bt + (size_t)nxt.pn * tstepB : cB;
;         for (int t = 0; t < nt; t += 2) {
;             const bool last = (t == nt - 2);
;             const char* a1 = cA + (size_t)(t + 1) * kstep;
;             const char* a2 = last ? nA : cA + (size_t)(t + 2) * kstep; const char* b2 = last ? nB : cB + (size_t)(t + 2) * kstep;
;             const char* a3 = a2 + kstep; const char* b3 = b2 + kstep;
;             PG8_LDB(B0, 0, 0); PG8_LDB(B1, 0, 1); PG8_SCHED; PG8_LDA(At, 0, 0); PG8_STAGE(PG8_SA(1, 1), a1 + hstepA, voffA);
;             PG8_WAIT_V(8); PG8_WAIT_L(0); PG8_BAR; PG8_MMA(0, 0, At, B0); PG8_MMA(0, 1, At, B1); PG8_BAR; PG8_SCHED;
;             PG8_LDA(At, 0, 1); PG8_STAGE(PG8_SB(0, 0), b2, voffB); PG8_STAGE(PG8_SB(0, 1), b2 + hstepB, voffB); PG8_STAGE(PG8_SA(0, 0), a2, voffA);
;             PG8_WAIT_V(8); PG8_WAIT_L(0); PG8_BAR; PG8_MMA(1, 0, At, B0); PG8_MMA(1, 1, At, B1); PG8_BAR; PG8_SCHED;
.LBB0_705:
	s_ashr_i32 s19, s18, 31
	s_lshl_b64 s[20:21], s[18:19], 19
	s_add_u32 s20, s6, s20
	s_addc_u32 s21, s7, s21
	s_and_b64 s[22:23], s[46:47], exec
	s_cselect_b32 s19, s21, s41
	s_cselect_b32 s54, s20, s40
	s_ashr_i32 s17, s16, 31
	s_lshl_b64 s[22:23], s[16:17], 19
	s_add_u32 s22, s8, s22
	s_addc_u32 s23, s1, s23
	s_and_b64 s[50:51], s[46:47], exec
	s_cselect_b32 s17, s23, s49
	s_cselect_b32 s55, s22, s48
	s_add_u32 s40, s40, 0x40080
	s_addc_u32 s41, s41, 0
	s_add_u32 s56, s48, 0x100
	s_addc_u32 s57, s49, 0
	s_mov_b32 s58, -2
	s_waitcnt lgkmcnt(0)
	s_waitcnt vmcnt(0)
	s_add_u32 s48, s40, 0xfffc0080
	s_addc_u32 s49, s41, -1
	s_add_i32 s59, 0, 0x10000
	s_cmp_eq_u32 s58, 12
	s_cselect_b32 s51, s19, s49
	s_cselect_b32 s50, s54, s48
	s_cselect_b32 s49, s17, s57
	s_cselect_b32 s48, s55, s56
	s_add_i32 s62, 0, 0x14000
	v_add_u32_e32 v146, s59, v228
	v_add_u32_e32 v162, s62, v228
	ds_read_b128 v[130:133], v146
	ds_read_b128 v[138:141], v146 offset:1024
	ds_read_b128 v[142:145], v146 offset:2048
	ds_read_b128 v[146:149], v146 offset:3072
	ds_read_b128 v[150:153], v162
	ds_read_b128 v[154:157], v162 offset:1024
	ds_read_b128 v[158:161], v162 offset:2048
	ds_read_b128 v[162:165], v162 offset:3072
	v_lshl_add_u64 v[216:217], s[40:41], 0, v[198:199]
	s_add_i32 m0, s30, 0xc000
	ds_read_b128 v[166:169], v244
	ds_read_b128 v[170:173], v244 offset:1024
	ds_read_b128 v[174:177], v244 offset:2048
	ds_read_b128 v[178:181], v244 offset:3072
	ds_read_b128 v[182:185], v244 offset:4096
	ds_read_b128 v[186:189], v244 offset:5120
	ds_read_b128 v[190:193], v244 offset:6144
	ds_read_b128 v[212:215], v244 offset:7168
	global_load_lds_dwordx4 v[216:217], off
	v_lshl_add_u64 v[216:217], s[40:41], 0, v[200:201]
	s_add_i32 m0, s30, 0xe000
	s_nop 0
	global_load_lds_dwordx4 v[216:217], off
	s_waitcnt vmcnt(8)
	s_waitcnt lgkmcnt(0)
	s_setprio 1
	s_barrier
	v_mfma_f32_16x16x32_bf16 v[134:137], v[130:133], v[166:169], 0
	v_mfma_f32_16x16x32_bf16 v[126:129], v[142:145], v[166:169], 0
	v_mfma_f32_16x16x32_bf16 v[114:117], v[130:133], v[174:177], 0
	v_mfma_f32_16x16x32_bf16 v[110:113], v[142:145], v[174:177], 0
	v_mfma_f32_16x16x32_bf16 v[98:101], v[130:133], v[182:185], 0
	v_mfma_f32_16x16x32_bf16 v[94:97], v[142:145], v[182:185], 0
	v_mfma_f32_16x16x32_bf16 v[82:85], v[130:133], v[190:193], 0
	v_mfma_f32_16x16x32_bf16 v[78:81], v[142:145], v[190:193], 0
	v_mfma_f32_16x16x32_bf16 v[134:137], v[138:141], v[170:173], v[134:137]
	v_mfma_f32_16x16x32_bf16 v[126:129], v[146:149], v[170:173], v[126:129]
	v_mfma_f32_16x16x32_bf16 v[114:117], v[138:141], v[178:181], v[114:117]
	v_mfma_f32_16x16x32_bf16 v[110:113], v[146:149], v[178:181], v[110:113]
	v_mfma_f32_16x16x32_bf16 v[98:101], v[138:141], v[186:189], v[98:101]
	v_mfma_f32_16x16x32_bf16 v[94:97], v[146:149], v[186:189], v[94:97]
	v_mfma_f32_16x16x32_bf16 v[82:85], v[138:141], v[212:215], v[82:85]
	v_mfma_f32_16x16x32_bf16 v[78:81], v[146:149], v[212:215], v[78:81]
	s_setprio 0
	s_setprio 1
	v_mfma_f32_16x16x32_bf16 v[122:125], v[150:153], v[166:169], 0
	v_mfma_f32_16x16x32_bf16 v[118:121], v[158:161], v[166:169], 0
	v_mfma_f32_16x16x32_bf16 v[106:109], v[150:153], v[174:177], 0
	v_mfma_f32_16x16x32_bf16 v[102:105], v[158:161], v[174:177], 0
	v_mfma_f32_16x16x32_bf16 v[90:93], v[150:153], v[182:185], 0
	v_mfma_f32_16x16x32_bf16 v[86:89], v[158:161], v[182:185], 0
	v_mfma_f32_16x16x32_bf16 v[74:77], v[150:153], v[190:193], 0
	v_mfma_f32_16x16x32_bf16 v[70:73], v[158:161], v[190:193], 0
	v_mfma_f32_16x16x32_bf16 v[122:125], v[154:157], v[170:173], v[122:125]
	v_mfma_f32_16x16x32_bf16 v[118:121], v[162:165], v[170:173], v[118:121]
	v_mfma_f32_16x16x32_bf16 v[106:109], v[154:157], v[178:181], v[106:109]
	v_mfma_f32_16x16x32_bf16 v[102:105], v[162:165], v[178:181], v[102:105]
	v_mfma_f32_16x16x32_bf16 v[90:93], v[154:157], v[186:189], v[90:93]
	v_mfma_f32_16x16x32_bf16 v[86:89], v[162:165], v[186:189], v[86:89]
	v_mfma_f32_16x16x32_bf16 v[74:77], v[154:157], v[212:215], v[74:77]
	v_mfma_f32_16x16x32_bf16 v[70:73], v[162:165], v[212:215], v[70:73]
	s_barrier
	s_setprio 0
	s_add_i32 s59, s59, s9
	v_lshl_add_u64 v[216:217], s[48:49], 0, v[0:1]
	s_mov_b32 m0, s59
	ds_read_b128 v[166:169], v244 offset:16384
	ds_read_b128 v[170:173], v244 offset:17408
	ds_read_b128 v[174:177], v244 offset:18432
	ds_read_b128 v[178:181], v244 offset:19456
	ds_read_b128 v[182:185], v244 offset:20480
	ds_read_b128 v[186:189], v244 offset:21504
	ds_read_b128 v[190:193], v244 offset:22528
	ds_read_b128 v[212:215], v244 offset:23552
	global_load_lds_dwordx4 v[216:217], off
	s_add_i32 m0, s59, 0x2000
	s_add_u32 s60, s48, 0x40000
	v_lshl_add_u64 v[218:219], s[48:49], 0, v[14:15]
	s_addc_u32 s61, s49, 0
	s_add_i32 s59, s62, s9
	global_load_lds_dwordx4 v[218:219], off
	v_lshl_add_u64 v[220:221], s[60:61], 0, v[0:1]
	s_mov_b32 m0, s59
	v_lshl_add_u64 v[222:223], s[50:51], 0, v[194:195]
	global_load_lds_dwordx4 v[220:221], off
	v_lshl_add_u64 v[220:221], s[60:61], 0, v[14:15]
	s_add_i32 m0, s59, 0x2000
	s_nop 0
	global_load_lds_dwordx4 v[220:221], off
	v_lshl_add_u64 v[220:221], s[50:51], 0, v[196:197]
	s_mov_b32 m0, s30
	s_nop 0
	global_load_lds_dwordx4 v[220:221], off
	s_mov_b32 m0, s31
	s_nop 0
	global_load_lds_dwordx4 v[222:223], off
	s_waitcnt vmcnt(8)
	s_waitcnt lgkmcnt(0)
	s_setprio 1
	s_barrier
; #define PG8_STAGE(bufoff, gbase, voff) do { _Pragma("unroll") for (int _i = 0; _i < 2; ++_i) \
;         __builtin_amdgcn_global_load_lds((const unsigned*)((const char*)(gbase) + (voff)[_i]), (LAS unsigned*)(lds + (bufoff) + ldsw + _i * 8192), 16, 0, 0); } while (0)
; #define PG8_LDA(dst, b, h) do { _Pragma("unroll") for (int m = 0; m < 4; ++m) _Pragma("unroll") for (int k = 0; k < 2; ++k) dst[m][k] = *(const LAS bf16x8*)(lds + PG8_SA(b, h) + aoff + m * 2048 + k * 1024); } while (0)
; #define PG8_LDB(dst, b, h) do { _Pragma("unroll") for (int n = 0; n < 2; ++n) _Pragma("unroll") for (int k = 0; k < 2; ++k) dst[n][k] = *(const LAS bf16x8*)(lds + PG8_SB(b, h) + boff + n * 2048 + k * 1024); } while (0)
; #define PG8_MMA(ai, bj, At, Bt) do { __builtin_amdgcn_s_setprio(1); _Pragma("unroll") for (int m = 0; m < 4; ++m) _Pragma("unroll") for (int n = 0; n < 2; ++n) _Pragma("unroll") for (int k = 0; k < 2; ++k) \
;         acc[ai][bj][m][n] = __builtin_amdgcn_mfma_f32_16x16x32_bf16(Bt[n][k], At[m][k], acc[ai][bj][m][n], 0, 0, 0); __builtin_amdgcn_s_setprio(0); } while (0)
; #define PG8_WAIT_V(n) asm volatile("s_waitcnt vmcnt(" #n ")" ::: "memory")
; #define PG8_WAIT_L(n) asm volatile("s_waitcnt lgkmcnt(" #n ")" ::: "memory")
; #define PG8_BAR __builtin_amdgcn_s_barrier()
; #define PG8_SCHED __builtin_amdgcn_sched_barrier(0)
; template <class Epi, bool SEG>
; __device__ __forceinline__ void gemm_phase(LAS unsigned char* lds, const Gemm g, const int G, const int cidx, const Epi& E) {
;     ...
;             PG8_WAIT_V(8); PG8_WAIT_L(0); PG8_BAR; PG8_MMA(1, 0, At, B0); PG8_MMA(1, 1, At, B1); PG8_BAR; PG8_SCHED;
;             PG8_LDB(B0, 1, 0); PG8_LDB(B1, 1, 1); PG8_SCHED; PG8_LDA(At, 1, 0); PG8_STAGE(PG8_SA(0, 1), a2 + hstepA, voffA);
;             PG8_WAIT_V(8); PG8_WAIT_L(0); PG8_BAR; PG8_MMA(0, 0, At, B0); PG8_MMA(0, 1, At, B1); PG8_BAR; PG8_SCHED;
;             PG8_LDA(At, 1, 1); PG8_STAGE(PG8_SB(1, 0), b3, voffB); PG8_STAGE(PG8_SB(1, 1), b3 + hstepB, voffB); PG8_STAGE(PG8_SA(1, 0), a3, voffA);
	v_mfma_f32_16x16x32_bf16 v[66:69], v[130:133], v[166:169], 0
	v_mfma_f32_16x16x32_bf16 v[62:65], v[142:145], v[166:169], 0
	v_mfma_f32_16x16x32_bf16 v[50:53], v[130:133], v[174:177], 0
	v_mfma_f32_16x16x32_bf16 v[46:49], v[142:145], v[174:177], 0
	v_mfma_f32_16x16x32_bf16 v[34:37], v[130:133], v[182:185], 0
	v_mfma_f32_16x16x32_bf16 v[30:33], v[142:145], v[182:185], 0
	v_mfma_f32_16x16x32_bf16 v[18:21], v[130:133], v[190:193], 0
	v_mfma_f32_16x16x32_bf16 v[10:13], v[142:145], v[190:193], 0
	v_mfma_f32_16x16x32_bf16 v[66:69], v[138:141], v[170:173], v[66:69]
	v_mfma_f32_16x16x32_bf16 v[62:65], v[146:149], v[170:173], v[62:65]
	v_mfma_f32_16x16x32_bf16 v[50:53], v[138:141], v[178:181], v[50:53]
	v_mfma_f32_16x16x32_bf16 v[46:49], v[146:149], v[178:181], v[46:49]
	v_mfma_f32_16x16x32_bf16 v[34:37], v[138:141], v[186:189], v[34:37]
	v_mfma_f32_16x16x32_bf16 v[30:33], v[146:149], v[186:189], v[30:33]
	v_mfma_f32_16x16x32_bf16 v[18:21], v[138:141], v[212:215], v[18:21]
	v_mfma_f32_16x16x32_bf16 v[10:13], v[146:149], v[212:215], v[10:13]
	s_setprio 0
	s_setprio 1
	v_mfma_f32_16x16x32_bf16 v[58:61], v[150:153], v[166:169], 0
	v_mfma_f32_16x16x32_bf16 v[54:57], v[158:161], v[166:169], 0
	v_mfma_f32_16x16x32_bf16 v[42:45], v[150:153], v[174:177], 0
	v_mfma_f32_16x16x32_bf16 v[38:41], v[158:161], v[174:177], 0
	v_mfma_f32_16x16x32_bf16 v[26:29], v[150:153], v[182:185], 0
	v_mfma_f32_16x16x32_bf16 v[22:25], v[158:161], v[182:185], 0
	v_mfma_f32_16x16x32_bf16 v[6:9], v[150:153], v[190:193], 0
	v_mfma_f32_16x16x32_bf16 v[2:5], v[158:161], v[190:193], 0
	v_mfma_f32_16x16x32_bf16 v[58:61], v[154:157], v[170:173], v[58:61]
	v_mfma_f32_16x16x32_bf16 v[54:57], v[162:165], v[170:173], v[54:57]
	v_mfma_f32_16x16x32_bf16 v[42:45], v[154:157], v[178:181], v[42:45]
	v_mfma_f32_16x16x32_bf16 v[38:41], v[162:165], v[178:181], v[38:41]
	v_mfma_f32_16x16x32_bf16 v[26:29], v[154:157], v[186:189], v[26:29]
	v_mfma_f32_16x16x32_bf16 v[22:25], v[162:165], v[186:189], v[22:25]
	v_mfma_f32_16x16x32_bf16 v[6:9], v[154:157], v[212:215], v[6:9]
	v_mfma_f32_16x16x32_bf16 v[2:5], v[162:165], v[212:215], v[2:5]
	s_barrier
	s_setprio 0
	s_add_i32 s59, 0, 0x18000
	s_add_i32 s60, 0, 0x1c000
	v_add_u32_e32 v146, s59, v228
	v_add_u32_e32 v162, s60, v228
	ds_read_b128 v[130:133], v146
	ds_read_b128 v[138:141], v146 offset:1024
	ds_read_b128 v[142:145], v146 offset:2048
	ds_read_b128 v[146:149], v146 offset:3072
	ds_read_b128 v[150:153], v162
	ds_read_b128 v[154:157], v162 offset:1024
	ds_read_b128 v[158:161], v162 offset:2048
	ds_read_b128 v[162:165], v162 offset:3072
	s_add_u32 s50, s50, 0x40000
	s_addc_u32 s51, s51, 0
	s_mov_b32 m0, s36
	v_lshl_add_u64 v[224:225], s[50:51], 0, v[196:197]
	ds_read_b128 v[166:169], v244 offset:32768
	ds_read_b128 v[170:173], v244 offset:33792
	ds_read_b128 v[174:177], v244 offset:34816
	ds_read_b128 v[178:181], v244 offset:35840
	ds_read_b128 v[182:185], v244 offset:36864
	ds_read_b128 v[186:189], v244 offset:37888
	ds_read_b128 v[190:193], v244 offset:38912
	ds_read_b128 v[212:215], v244 offset:39936
	global_load_lds_dwordx4 v[224:225], off
	v_lshl_add_u64 v[224:225], s[50:51], 0, v[194:195]
	s_mov_b32 m0, s38
	s_nop 0
	global_load_lds_dwordx4 v[224:225], off
	s_waitcnt vmcnt(8)
	s_waitcnt lgkmcnt(0)
	s_setprio 1
	s_barrier
	v_mfma_f32_16x16x32_bf16 v[134:137], v[130:133], v[166:169], v[134:137]
	v_mfma_f32_16x16x32_bf16 v[126:129], v[142:145], v[166:169], v[126:129]
	v_mfma_f32_16x16x32_bf16 v[114:117], v[130:133], v[174:177], v[114:117]
	v_mfma_f32_16x16x32_bf16 v[110:113], v[142:145], v[174:177], v[110:113]
	v_mfma_f32_16x16x32_bf16 v[98:101], v[130:133], v[182:185], v[98:101]
	v_mfma_f32_16x16x32_bf16 v[94:97], v[142:145], v[182:185], v[94:97]
	v_mfma_f32_16x16x32_bf16 v[82:85], v[130:133], v[190:193], v[82:85]
	v_mfma_f32_16x16x32_bf16 v[78:81], v[142:145], v[190:193], v[78:81]
	v_mfma_f32_16x16x32_bf16 v[134:137], v[138:141], v[170:173], v[134:137]
	v_mfma_f32_16x16x32_bf16 v[126:129], v[146:149], v[170:173], v[126:129]
	v_mfma_f32_16x16x32_bf16 v[114:117], v[138:141], v[178:181], v[114:117]
	v_mfma_f32_16x16x32_bf16 v[110:113], v[146:149], v[178:181], v[110:113]
	v_mfma_f32_16x16x32_bf16 v[98:101], v[138:141], v[186:189], v[98:101]
	v_mfma_f32_16x16x32_bf16 v[94:97], v[146:149], v[186:189], v[94:97]
	v_mfma_f32_16x16x32_bf16 v[82:85], v[138:141], v[212:215], v[82:85]
	v_mfma_f32_16x16x32_bf16 v[78:81], v[146:149], v[212:215], v[78:81]
	s_setprio 0
	s_setprio 1
	v_mfma_f32_16x16x32_bf16 v[122:125], v[150:153], v[166:169], v[122:125]
	v_mfma_f32_16x16x32_bf16 v[118:121], v[158:161], v[166:169], v[118:121]
	v_mfma_f32_16x16x32_bf16 v[106:109], v[150:153], v[174:177], v[106:109]
	v_mfma_f32_16x16x32_bf16 v[102:105], v[158:161], v[174:177], v[102:105]
	v_mfma_f32_16x16x32_bf16 v[90:93], v[150:153], v[182:185], v[90:93]
	v_mfma_f32_16x16x32_bf16 v[86:89], v[158:161], v[182:185], v[86:89]
	v_mfma_f32_16x16x32_bf16 v[74:77], v[150:153], v[190:193], v[74:77]
	v_mfma_f32_16x16x32_bf16 v[70:73], v[158:161], v[190:193], v[70:73]
	v_mfma_f32_16x16x32_bf16 v[122:125], v[154:157], v[170:173], v[122:125]
	v_mfma_f32_16x16x32_bf16 v[118:121], v[162:165], v[170:173], v[118:121]
	v_mfma_f32_16x16x32_bf16 v[106:109], v[154:157], v[178:181], v[106:109]
	v_mfma_f32_16x16x32_bf16 v[102:105], v[162:165], v[178:181], v[102:105]
	v_mfma_f32_16x16x32_bf16 v[90:93], v[154:157], v[186:189], v[90:93]
	v_mfma_f32_16x16x32_bf16 v[86:89], v[162:165], v[186:189], v[86:89]
	v_mfma_f32_16x16x32_bf16 v[74:77], v[154:157], v[212:215], v[74:77]
	v_mfma_f32_16x16x32_bf16 v[70:73], v[162:165], v[212:215], v[70:73]
	s_barrier
; #define PG8_STAGE(bufoff, gbase, voff) do { _Pragma("unroll") for (int _i = 0; _i < 2; ++_i) \
;         __builtin_amdgcn_global_load_lds((const unsigned*)((const char*)(gbase) + (voff)[_i]), (LAS unsigned*)(lds + (bufoff) + ldsw + _i * 8192), 16, 0, 0); } while (0)
; #define PG8_LDA(dst, b, h) do { _Pragma("unroll") for (int m = 0; m < 4; ++m) _Pragma("unroll") for (int k = 0; k < 2; ++k) dst[m][k] = *(const LAS bf16x8*)(lds + PG8_SA(b, h) + aoff + m * 2048 + k * 1024); } while (0)
; #define PG8_MMA(ai, bj, At, Bt) do { __builtin_amdgcn_s_setprio(1); _Pragma("unroll") for (int m = 0; m < 4; ++m) _Pragma("unroll") for (int n = 0; n < 2; ++n) _Pragma("unroll") for (int k = 0; k < 2; ++k) \
;         acc[ai][bj][m][n] = __builtin_amdgcn_mfma_f32_16x16x32_bf16(Bt[n][k], At[m][k], acc[ai][bj][m][n], 0, 0, 0); __builtin_amdgcn_s_setprio(0); } while (0)
; #define PG8_WAIT_V(n) asm volatile("s_waitcnt vmcnt(" #n ")" ::: "memory")
; #define PG8_WAIT_L(n) asm volatile("s_waitcnt lgkmcnt(" #n ")" ::: "memory")
; #define PG8_BAR __builtin_amdgcn_s_barrier()
; #define PG8_SCHED __builtin_amdgcn_sched_barrier(0)
; template <class Epi, bool SEG>
; __device__ __forceinline__ void gemm_phase(LAS unsigned char* lds, const Gemm g, const int G, const int cidx, const Epi& E) {
;     ...
;             PG8_LDA(At, 1, 1); PG8_STAGE(PG8_SB(1, 0), b3, voffB); PG8_STAGE(PG8_SB(1, 1), b3 + hstepB, voffB); PG8_STAGE(PG8_SA(1, 0), a3, voffA);
;             PG8_WAIT_V(8); PG8_WAIT_L(0); PG8_BAR; PG8_MMA(1, 0, At, B0); PG8_MMA(1, 1, At, B1); PG8_BAR; PG8_SCHED;
;         }
	s_setprio 0
	s_add_i32 s50, s59, s9
	v_lshl_add_u64 v[216:217], v[216:217], 0, s[28:29]
	s_mov_b32 m0, s50
	ds_read_b128 v[166:169], v244 offset:49152
	ds_read_b128 v[170:173], v244 offset:50176
	ds_read_b128 v[174:177], v244 offset:51200
	ds_read_b128 v[178:181], v244 offset:52224
	ds_read_b128 v[182:185], v244 offset:53248
	ds_read_b128 v[186:189], v244 offset:54272
	ds_read_b128 v[190:193], v244 offset:55296
	ds_read_b128 v[212:215], v244 offset:56320
	global_load_lds_dwordx4 v[216:217], off
	s_add_i32 m0, s50, 0x2000
	s_add_u32 s48, s48, 0x40080
	v_lshl_add_u64 v[216:217], v[218:219], 0, s[28:29]
	s_addc_u32 s49, s49, 0
	s_add_i32 s50, s60, s9
	global_load_lds_dwordx4 v[216:217], off
	v_lshl_add_u64 v[216:217], s[48:49], 0, v[0:1]
	s_mov_b32 m0, s50
	s_nop 0
	global_load_lds_dwordx4 v[216:217], off
	v_lshl_add_u64 v[216:217], s[48:49], 0, v[14:15]
	s_add_i32 m0, s50, 0x2000
	s_nop 0
	global_load_lds_dwordx4 v[216:217], off
	v_lshl_add_u64 v[216:217], v[220:221], 0, s[28:29]
	s_mov_b32 m0, s39
	s_nop 0
	global_load_lds_dwordx4 v[216:217], off
	v_lshl_add_u64 v[216:217], v[222:223], 0, s[28:29]
	s_mov_b32 m0, s52
	s_nop 0
	global_load_lds_dwordx4 v[216:217], off
	s_waitcnt vmcnt(8)
	s_waitcnt lgkmcnt(0)
	s_setprio 1
	s_barrier
	v_mfma_f32_16x16x32_bf16 v[66:69], v[130:133], v[166:169], v[66:69]
	v_mfma_f32_16x16x32_bf16 v[62:65], v[142:145], v[166:169], v[62:65]
	v_mfma_f32_16x16x32_bf16 v[50:53], v[130:133], v[174:177], v[50:53]
	v_mfma_f32_16x16x32_bf16 v[46:49], v[142:145], v[174:177], v[46:49]
	v_mfma_f32_16x16x32_bf16 v[34:37], v[130:133], v[182:185], v[34:37]
	v_mfma_f32_16x16x32_bf16 v[30:33], v[142:145], v[182:185], v[30:33]
	v_mfma_f32_16x16x32_bf16 v[18:21], v[130:133], v[190:193], v[18:21]
	v_mfma_f32_16x16x32_bf16 v[10:13], v[142:145], v[190:193], v[10:13]
	v_mfma_f32_16x16x32_bf16 v[66:69], v[138:141], v[170:173], v[66:69]
	v_mfma_f32_16x16x32_bf16 v[62:65], v[146:149], v[170:173], v[62:65]
	v_mfma_f32_16x16x32_bf16 v[50:53], v[138:141], v[178:181], v[50:53]
	v_mfma_f32_16x16x32_bf16 v[46:49], v[146:149], v[178:181], v[46:49]
	v_mfma_f32_16x16x32_bf16 v[34:37], v[138:141], v[186:189], v[34:37]
	v_mfma_f32_16x16x32_bf16 v[30:33], v[146:149], v[186:189], v[30:33]
	v_mfma_f32_16x16x32_bf16 v[18:21], v[138:141], v[212:215], v[18:21]
	v_mfma_f32_16x16x32_bf16 v[10:13], v[146:149], v[212:215], v[10:13]
	s_setprio 0
	s_setprio 1
	v_mfma_f32_16x16x32_bf16 v[58:61], v[150:153], v[166:169], v[58:61]
	v_mfma_f32_16x16x32_bf16 v[54:57], v[158:161], v[166:169], v[54:57]
	v_mfma_f32_16x16x32_bf16 v[42:45], v[150:153], v[174:177], v[42:45]
	v_mfma_f32_16x16x32_bf16 v[38:41], v[158:161], v[174:177], v[38:41]
	v_mfma_f32_16x16x32_bf16 v[26:29], v[150:153], v[182:185], v[26:29]
	v_mfma_f32_16x16x32_bf16 v[22:25], v[158:161], v[182:185], v[22:25]
	v_mfma_f32_16x16x32_bf16 v[6:9], v[150:153], v[190:193], v[6:9]
	v_mfma_f32_16x16x32_bf16 v[2:5], v[158:161], v[190:193], v[2:5]
	v_mfma_f32_16x16x32_bf16 v[58:61], v[154:157], v[170:173], v[58:61]
	v_mfma_f32_16x16x32_bf16 v[54:57], v[162:165], v[170:173], v[54:57]
	v_mfma_f32_16x16x32_bf16 v[42:45], v[154:157], v[178:181], v[42:45]
	v_mfma_f32_16x16x32_bf16 v[38:41], v[162:165], v[178:181], v[38:41]
	v_mfma_f32_16x16x32_bf16 v[26:29], v[154:157], v[186:189], v[26:29]
	v_mfma_f32_16x16x32_bf16 v[22:25], v[162:165], v[186:189], v[22:25]
	v_mfma_f32_16x16x32_bf16 v[6:9], v[154:157], v[212:215], v[6:9]
	v_mfma_f32_16x16x32_bf16 v[2:5], v[162:165], v[212:215], v[2:5]
	s_barrier
	s_setprio 0
	s_add_i32 s58, s58, 2
	s_add_u32 s40, s40, 0x100
	s_addc_u32 s41, s41, 0
	s_add_u32 s56, s56, 0x100
	s_addc_u32 s57, s57, 0

; #define PG8_STAGE(bufoff, gbase, voff) do { _Pragma("unroll") for (int _i = 0; _i < 2; ++_i) \
;         __builtin_amdgcn_global_load_lds((const unsigned*)((const char*)(gbase) + (voff)[_i]), (LAS unsigned*)(lds + (bufoff) + ldsw + _i * 8192), 16, 0, 0); } while (0)
; #define PG8_LDA(dst, b, h) do { _Pragma("unroll") for (int m = 0; m < 4; ++m) _Pragma("unroll") for (int k = 0; k < 2; ++k) dst[m][k] = *(const LAS bf16x8*)(lds + PG8_SA(b, h) + aoff + m * 2048 + k * 1024); } while (0)
; #define PG8_LDB(dst, b, h) do { _Pragma("unroll") for (int n = 0; n < 2; ++n) _Pragma("unroll") for (int k = 0; k < 2; ++k) dst[n][k] = *(const LAS bf16x8*)(lds + PG8_SB(b, h) + boff + n * 2048 + k * 1024); } while (0)
; #define PG8_MMA(ai, bj, At, Bt) do { __builtin_amdgcn_s_setprio(1); _Pragma("unroll") for (int m = 0; m < 4; ++m) _Pragma("unroll") for (int n = 0; n < 2; ++n) _Pragma("unroll") for (int k = 0; k < 2; ++k) \
;         acc[ai][bj][m][n] = __builtin_amdgcn_mfma_f32_16x16x32_bf16(Bt[n][k], At[m][k], acc[ai][bj][m][n], 0, 0, 0); __builtin_amdgcn_s_setprio(0); } while (0)
; #define PG8_BAR __builtin_amdgcn_s_barrier()
; template <class Epi, bool SEG>
; __device__ __forceinline__ void gemm_phase(LAS unsigned char* lds, const Gemm g, const int G, const int cidx, const Epi& E) {
;     ...
;         const bool has_next = S.next(ui + 1, nxt);
;         const char* nA = has_next ? (const char*)g.A + (long)nxt.pm * (long)tstepA + aoff0 : cA; const char* nB = has_next ? (const char*)g.Bt + (size_t)nxt.pn * tstepB : cB;
;         for (int t = 0; t < nt; t += 2) {
;             const bool last = (t == nt - 2);
;             const char* a1 = cA + (size_t)(t + 1) * kstep;
;             const char* a2 = last ? nA : cA + (size_t)(t + 2) * kstep; const char* b2 = last ? nB : cB + (size_t)(t + 2) * kstep;
;             const char* a3 = a2 + kstep; const char* b3 = b2 + kstep;
;             PG8_LDB(B0, 0, 0); PG8_LDB(B1, 0, 1); PG8_SCHED; PG8_LDA(At, 0, 0); PG8_STAGE(PG8_SA(1, 1), a1 + hstepA, voffA);
;             PG8_WAIT_V(8); PG8_WAIT_L(0); PG8_BAR; PG8_MMA(0, 0, At, B0); PG8_MMA(0, 1, At, B1); PG8_BAR; PG8_SCHED;
;             PG8_LDA(At, 0, 1); PG8_STAGE(PG8_SB(0, 0), b2, voffB); PG8_STAGE(PG8_SB(0, 1), b2 + hstepB, voffB); PG8_STAGE(PG8_SA(0, 0), a2, voffA);
;             PG8_WAIT_V(8); PG8_WAIT_L(0); PG8_BAR; PG8_MMA(1, 0, At, B0); PG8_MMA(1, 1, At, B1); PG8_BAR; PG8_SCHED;
.LBB0_785:
	s_ashr_i32 s15, s14, 31
	s_lshl_b64 s[18:19], s[14:15], 19
	v_readlane_b32 s15, v255, 15
	s_add_u32 s18, s15, s18
	v_readlane_b32 s15, v255, 16
	s_addc_u32 s19, s15, s19
	s_and_b64 s[6:7], s[6:7], exec
	s_cselect_b32 s15, s19, s23
	s_cselect_b32 s21, s18, s22
	s_add_u32 s6, s40, 0x3e080
	s_addc_u32 s7, s41, 0
	s_add_u32 s52, s22, 0x100
	s_addc_u32 s53, s23, 0
	s_mov_b32 s54, -2
	s_waitcnt vmcnt(0)
	s_add_u32 s22, s6, 0xfffc2080
	s_addc_u32 s23, s7, -1
	s_add_i32 s55, 0, 0x10000
	s_cmp_eq_u32 s54, 12
	s_cselect_b32 s41, s17, s23
	s_cselect_b32 s40, s16, s22
	s_cselect_b32 s23, s15, s53
	s_cselect_b32 s22, s21, s52
	s_add_i32 s58, 0, 0x14000
	v_add_u32_e32 v114, s55, v243
	v_add_u32_e32 v130, s58, v243
	ds_read_b128 v[102:105], v114
	ds_read_b128 v[106:109], v114 offset:1024
	ds_read_b128 v[110:113], v114 offset:2048
	ds_read_b128 v[114:117], v114 offset:3072
	ds_read_b128 v[118:121], v130
	ds_read_b128 v[122:125], v130 offset:1024
	ds_read_b128 v[126:129], v130 offset:2048
	ds_read_b128 v[130:133], v130 offset:3072
	v_lshl_add_u64 v[208:209], s[6:7], 0, v[198:199]
	s_add_i32 m0, s11, 0xc000
	ds_read_b128 v[166:169], v247
	ds_read_b128 v[170:173], v247 offset:1024
	ds_read_b128 v[174:177], v247 offset:2048
	ds_read_b128 v[178:181], v247 offset:3072
	ds_read_b128 v[182:185], v247 offset:4096
	ds_read_b128 v[186:189], v247 offset:5120
	ds_read_b128 v[212:215], v247 offset:6144
	ds_read_b128 v[216:219], v247 offset:7168
	global_load_lds_dwordx4 v[208:209], off
	v_lshl_add_u64 v[208:209], s[6:7], 0, v[200:201]
	s_add_i32 m0, s11, 0xe000
	s_nop 0
	global_load_lds_dwordx4 v[208:209], off
	s_waitcnt vmcnt(8)
	s_waitcnt lgkmcnt(0)
	s_setprio 1
	s_barrier
	v_mfma_f32_16x16x32_bf16 v[162:165], v[102:105], v[166:169], 0
	v_mfma_f32_16x16x32_bf16 v[66:69], v[110:113], v[166:169], 0
	v_mfma_f32_16x16x32_bf16 v[158:161], v[102:105], v[174:177], 0
	v_mfma_f32_16x16x32_bf16 v[62:65], v[110:113], v[174:177], 0
	v_mfma_f32_16x16x32_bf16 v[146:149], v[102:105], v[182:185], 0
	v_mfma_f32_16x16x32_bf16 v[50:53], v[110:113], v[182:185], 0
	v_mfma_f32_16x16x32_bf16 v[138:141], v[102:105], v[212:215], 0
	v_mfma_f32_16x16x32_bf16 v[42:45], v[110:113], v[212:215], 0
	v_mfma_f32_16x16x32_bf16 v[162:165], v[106:109], v[170:173], v[162:165]
	v_mfma_f32_16x16x32_bf16 v[66:69], v[114:117], v[170:173], v[66:69]
	v_mfma_f32_16x16x32_bf16 v[158:161], v[106:109], v[178:181], v[158:161]
	v_mfma_f32_16x16x32_bf16 v[62:65], v[114:117], v[178:181], v[62:65]
	v_mfma_f32_16x16x32_bf16 v[146:149], v[106:109], v[186:189], v[146:149]
	v_mfma_f32_16x16x32_bf16 v[50:53], v[114:117], v[186:189], v[50:53]
	v_mfma_f32_16x16x32_bf16 v[138:141], v[106:109], v[216:219], v[138:141]
	v_mfma_f32_16x16x32_bf16 v[42:45], v[114:117], v[216:219], v[42:45]
	s_setprio 0
	s_setprio 1
	v_mfma_f32_16x16x32_bf16 v[154:157], v[118:121], v[166:169], 0
	v_mfma_f32_16x16x32_bf16 v[58:61], v[126:129], v[166:169], 0
	v_mfma_f32_16x16x32_bf16 v[150:153], v[118:121], v[174:177], 0
	v_mfma_f32_16x16x32_bf16 v[54:57], v[126:129], v[174:177], 0
	v_mfma_f32_16x16x32_bf16 v[142:145], v[118:121], v[182:185], 0
	v_mfma_f32_16x16x32_bf16 v[46:49], v[126:129], v[182:185], 0
	v_mfma_f32_16x16x32_bf16 v[134:137], v[118:121], v[212:215], 0
	v_mfma_f32_16x16x32_bf16 v[38:41], v[126:129], v[212:215], 0
	v_mfma_f32_16x16x32_bf16 v[154:157], v[122:125], v[170:173], v[154:157]
	v_mfma_f32_16x16x32_bf16 v[58:61], v[130:133], v[170:173], v[58:61]
	v_mfma_f32_16x16x32_bf16 v[150:153], v[122:125], v[178:181], v[150:153]
	v_mfma_f32_16x16x32_bf16 v[54:57], v[130:133], v[178:181], v[54:57]
	v_mfma_f32_16x16x32_bf16 v[142:145], v[122:125], v[186:189], v[142:145]
	v_mfma_f32_16x16x32_bf16 v[46:49], v[130:133], v[186:189], v[46:49]
	v_mfma_f32_16x16x32_bf16 v[134:137], v[122:125], v[216:219], v[134:137]
	v_mfma_f32_16x16x32_bf16 v[38:41], v[130:133], v[216:219], v[38:41]
	s_barrier
	s_setprio 0
	s_add_i32 s55, s55, s10
	v_lshl_add_u64 v[208:209], s[22:23], 0, v[0:1]
	s_mov_b32 m0, s55
	ds_read_b128 v[166:169], v247 offset:16384
	ds_read_b128 v[170:173], v247 offset:17408
	ds_read_b128 v[174:177], v247 offset:18432
	ds_read_b128 v[178:181], v247 offset:19456
	ds_read_b128 v[182:185], v247 offset:20480
	ds_read_b128 v[186:189], v247 offset:21504
	ds_read_b128 v[212:215], v247 offset:22528
	ds_read_b128 v[216:219], v247 offset:23552
	global_load_lds_dwordx4 v[208:209], off
	s_add_i32 m0, s55, 0x2000
	s_add_u32 s56, s22, 0x40000
	v_lshl_add_u64 v[220:221], s[22:23], 0, v[192:193]
	s_addc_u32 s57, s23, 0
	s_add_i32 s55, s58, s10
	global_load_lds_dwordx4 v[220:221], off
	v_lshl_add_u64 v[222:223], s[56:57], 0, v[0:1]
	s_mov_b32 m0, s55
	v_lshl_add_u64 v[224:225], s[40:41], 0, v[190:191]
	global_load_lds_dwordx4 v[222:223], off
	v_lshl_add_u64 v[222:223], s[56:57], 0, v[192:193]
	s_add_i32 m0, s55, 0x2000
	s_nop 0
	global_load_lds_dwordx4 v[222:223], off
	v_lshl_add_u64 v[222:223], s[40:41], 0, v[14:15]
	s_mov_b32 m0, s11
	s_nop 0
	global_load_lds_dwordx4 v[222:223], off
	s_mov_b32 m0, s9
	s_nop 0
	global_load_lds_dwordx4 v[224:225], off
	s_waitcnt vmcnt(8)
	s_waitcnt lgkmcnt(0)
	s_setprio 1
	s_barrier
; #define PG8_STAGE(bufoff, gbase, voff) do { _Pragma("unroll") for (int _i = 0; _i < 2; ++_i) \
;         __builtin_amdgcn_global_load_lds((const unsigned*)((const char*)(gbase) + (voff)[_i]), (LAS unsigned*)(lds + (bufoff) + ldsw + _i * 8192), 16, 0, 0); } while (0)
; #define PG8_LDA(dst, b, h) do { _Pragma("unroll") for (int m = 0; m < 4; ++m) _Pragma("unroll") for (int k = 0; k < 2; ++k) dst[m][k] = *(const LAS bf16x8*)(lds + PG8_SA(b, h) + aoff + m * 2048 + k * 1024); } while (0)
; #define PG8_LDB(dst, b, h) do { _Pragma("unroll") for (int n = 0; n < 2; ++n) _Pragma("unroll") for (int k = 0; k < 2; ++k) dst[n][k] = *(const LAS bf16x8*)(lds + PG8_SB(b, h) + boff + n * 2048 + k * 1024); } while (0)
; #define PG8_MMA(ai, bj, At, Bt) do { __builtin_amdgcn_s_setprio(1); _Pragma("unroll") for (int m = 0; m < 4; ++m) _Pragma("unroll") for (int n = 0; n < 2; ++n) _Pragma("unroll") for (int k = 0; k < 2; ++k) \
;         acc[ai][bj][m][n] = __builtin_amdgcn_mfma_f32_16x16x32_bf16(Bt[n][k], At[m][k], acc[ai][bj][m][n], 0, 0, 0); __builtin_amdgcn_s_setprio(0); } while (0)
; #define PG8_WAIT_V(n) asm volatile("s_waitcnt vmcnt(" #n ")" ::: "memory")
; #define PG8_WAIT_L(n) asm volatile("s_waitcnt lgkmcnt(" #n ")" ::: "memory")
; #define PG8_BAR __builtin_amdgcn_s_barrier()
; #define PG8_SCHED __builtin_amdgcn_sched_barrier(0)
; template <class Epi, bool SEG>
; __device__ __forceinline__ void gemm_phase(LAS unsigned char* lds, const Gemm g, const int G, const int cidx, const Epi& E) {
;     ...
;             PG8_WAIT_V(8); PG8_WAIT_L(0); PG8_BAR; PG8_MMA(1, 0, At, B0); PG8_MMA(1, 1, At, B1); PG8_BAR; PG8_SCHED;
;             PG8_LDB(B0, 1, 0); PG8_LDB(B1, 1, 1); PG8_SCHED; PG8_LDA(At, 1, 0); PG8_STAGE(PG8_SA(0, 1), a2 + hstepA, voffA);
;             PG8_WAIT_V(8); PG8_WAIT_L(0); PG8_BAR; PG8_MMA(0, 0, At, B0); PG8_MMA(0, 1, At, B1); PG8_BAR; PG8_SCHED;
;             PG8_LDA(At, 1, 1); PG8_STAGE(PG8_SB(1, 0), b3, voffB); PG8_STAGE(PG8_SB(1, 1), b3 + hstepB, voffB); PG8_STAGE(PG8_SA(1, 0), a3, voffA);
	v_mfma_f32_16x16x32_bf16 v[98:101], v[102:105], v[166:169], 0
	v_mfma_f32_16x16x32_bf16 v[34:37], v[110:113], v[166:169], 0
	v_mfma_f32_16x16x32_bf16 v[94:97], v[102:105], v[174:177], 0
	v_mfma_f32_16x16x32_bf16 v[30:33], v[110:113], v[174:177], 0
	v_mfma_f32_16x16x32_bf16 v[82:85], v[102:105], v[182:185], 0
	v_mfma_f32_16x16x32_bf16 v[18:21], v[110:113], v[182:185], 0
	v_mfma_f32_16x16x32_bf16 v[74:77], v[102:105], v[212:215], 0
	v_mfma_f32_16x16x32_bf16 v[6:9], v[110:113], v[212:215], 0
	v_mfma_f32_16x16x32_bf16 v[98:101], v[106:109], v[170:173], v[98:101]
	v_mfma_f32_16x16x32_bf16 v[34:37], v[114:117], v[170:173], v[34:37]
	v_mfma_f32_16x16x32_bf16 v[94:97], v[106:109], v[178:181], v[94:97]
	v_mfma_f32_16x16x32_bf16 v[30:33], v[114:117], v[178:181], v[30:33]
	v_mfma_f32_16x16x32_bf16 v[82:85], v[106:109], v[186:189], v[82:85]
	v_mfma_f32_16x16x32_bf16 v[18:21], v[114:117], v[186:189], v[18:21]
	v_mfma_f32_16x16x32_bf16 v[74:77], v[106:109], v[216:219], v[74:77]
	v_mfma_f32_16x16x32_bf16 v[6:9], v[114:117], v[216:219], v[6:9]
	s_setprio 0
	s_setprio 1
	v_mfma_f32_16x16x32_bf16 v[90:93], v[118:121], v[166:169], 0
	v_mfma_f32_16x16x32_bf16 v[26:29], v[126:129], v[166:169], 0
	v_mfma_f32_16x16x32_bf16 v[86:89], v[118:121], v[174:177], 0
	v_mfma_f32_16x16x32_bf16 v[22:25], v[126:129], v[174:177], 0
	v_mfma_f32_16x16x32_bf16 v[78:81], v[118:121], v[182:185], 0
	v_mfma_f32_16x16x32_bf16 v[10:13], v[126:129], v[182:185], 0
	v_mfma_f32_16x16x32_bf16 v[70:73], v[118:121], v[212:215], 0
	v_mfma_f32_16x16x32_bf16 v[2:5], v[126:129], v[212:215], 0
	v_mfma_f32_16x16x32_bf16 v[90:93], v[122:125], v[170:173], v[90:93]
	v_mfma_f32_16x16x32_bf16 v[26:29], v[130:133], v[170:173], v[26:29]
	v_mfma_f32_16x16x32_bf16 v[86:89], v[122:125], v[178:181], v[86:89]
	v_mfma_f32_16x16x32_bf16 v[22:25], v[130:133], v[178:181], v[22:25]
	v_mfma_f32_16x16x32_bf16 v[78:81], v[122:125], v[186:189], v[78:81]
	v_mfma_f32_16x16x32_bf16 v[10:13], v[130:133], v[186:189], v[10:13]
	v_mfma_f32_16x16x32_bf16 v[70:73], v[122:125], v[216:219], v[70:73]
	v_mfma_f32_16x16x32_bf16 v[2:5], v[130:133], v[216:219], v[2:5]
	s_barrier
	s_setprio 0
	s_add_i32 s55, 0, 0x18000
	s_add_i32 s56, 0, 0x1c000
	v_add_u32_e32 v114, s55, v243
	v_add_u32_e32 v130, s56, v243
	ds_read_b128 v[102:105], v114
	ds_read_b128 v[106:109], v114 offset:1024
	ds_read_b128 v[110:113], v114 offset:2048
	ds_read_b128 v[114:117], v114 offset:3072
	ds_read_b128 v[118:121], v130
	ds_read_b128 v[122:125], v130 offset:1024
	ds_read_b128 v[126:129], v130 offset:2048
	ds_read_b128 v[130:133], v130 offset:3072
	s_add_u32 s40, s40, 0x3e000
	s_addc_u32 s41, s41, 0
	s_mov_b32 m0, s36
	v_lshl_add_u64 v[226:227], s[40:41], 0, v[14:15]
	ds_read_b128 v[166:169], v247 offset:32768
	ds_read_b128 v[170:173], v247 offset:33792
	ds_read_b128 v[174:177], v247 offset:34816
	ds_read_b128 v[178:181], v247 offset:35840
	ds_read_b128 v[182:185], v247 offset:36864
	ds_read_b128 v[186:189], v247 offset:37888
	ds_read_b128 v[212:215], v247 offset:38912
	ds_read_b128 v[216:219], v247 offset:39936
	global_load_lds_dwordx4 v[226:227], off
	v_lshl_add_u64 v[226:227], s[40:41], 0, v[190:191]
	s_mov_b32 m0, s12
	s_nop 0
	global_load_lds_dwordx4 v[226:227], off
	s_waitcnt vmcnt(8)
	s_waitcnt lgkmcnt(0)
	s_setprio 1
	s_barrier
	v_mfma_f32_16x16x32_bf16 v[162:165], v[102:105], v[166:169], v[162:165]
	v_mfma_f32_16x16x32_bf16 v[66:69], v[110:113], v[166:169], v[66:69]
	v_mfma_f32_16x16x32_bf16 v[158:161], v[102:105], v[174:177], v[158:161]
	v_mfma_f32_16x16x32_bf16 v[62:65], v[110:113], v[174:177], v[62:65]
	v_mfma_f32_16x16x32_bf16 v[146:149], v[102:105], v[182:185], v[146:149]
	v_mfma_f32_16x16x32_bf16 v[50:53], v[110:113], v[182:185], v[50:53]
	v_mfma_f32_16x16x32_bf16 v[138:141], v[102:105], v[212:215], v[138:141]
	v_mfma_f32_16x16x32_bf16 v[42:45], v[110:113], v[212:215], v[42:45]
	v_mfma_f32_16x16x32_bf16 v[162:165], v[106:109], v[170:173], v[162:165]
	v_mfma_f32_16x16x32_bf16 v[66:69], v[114:117], v[170:173], v[66:69]
	v_mfma_f32_16x16x32_bf16 v[158:161], v[106:109], v[178:181], v[158:161]
	v_mfma_f32_16x16x32_bf16 v[62:65], v[114:117], v[178:181], v[62:65]
	v_mfma_f32_16x16x32_bf16 v[146:149], v[106:109], v[186:189], v[146:149]
	v_mfma_f32_16x16x32_bf16 v[50:53], v[114:117], v[186:189], v[50:53]
	v_mfma_f32_16x16x32_bf16 v[138:141], v[106:109], v[216:219], v[138:141]
	v_mfma_f32_16x16x32_bf16 v[42:45], v[114:117], v[216:219], v[42:45]
	s_setprio 0
	s_setprio 1
	v_mfma_f32_16x16x32_bf16 v[154:157], v[118:121], v[166:169], v[154:157]
	v_mfma_f32_16x16x32_bf16 v[58:61], v[126:129], v[166:169], v[58:61]
	v_mfma_f32_16x16x32_bf16 v[150:153], v[118:121], v[174:177], v[150:153]
	v_mfma_f32_16x16x32_bf16 v[54:57], v[126:129], v[174:177], v[54:57]
	v_mfma_f32_16x16x32_bf16 v[142:145], v[118:121], v[182:185], v[142:145]
	v_mfma_f32_16x16x32_bf16 v[46:49], v[126:129], v[182:185], v[46:49]
	v_mfma_f32_16x16x32_bf16 v[134:137], v[118:121], v[212:215], v[134:137]
	v_mfma_f32_16x16x32_bf16 v[38:41], v[126:129], v[212:215], v[38:41]
	v_mfma_f32_16x16x32_bf16 v[154:157], v[122:125], v[170:173], v[154:157]
	v_mfma_f32_16x16x32_bf16 v[58:61], v[130:133], v[170:173], v[58:61]
	v_mfma_f32_16x16x32_bf16 v[150:153], v[122:125], v[178:181], v[150:153]
	v_mfma_f32_16x16x32_bf16 v[54:57], v[130:133], v[178:181], v[54:57]
	v_mfma_f32_16x16x32_bf16 v[142:145], v[122:125], v[186:189], v[142:145]
	v_mfma_f32_16x16x32_bf16 v[46:49], v[130:133], v[186:189], v[46:49]
	v_mfma_f32_16x16x32_bf16 v[134:137], v[122:125], v[216:219], v[134:137]
	v_mfma_f32_16x16x32_bf16 v[38:41], v[130:133], v[216:219], v[38:41]
	s_barrier
; #define PG8_STAGE(bufoff, gbase, voff) do { _Pragma("unroll") for (int _i = 0; _i < 2; ++_i) \
;         __builtin_amdgcn_global_load_lds((const unsigned*)((const char*)(gbase) + (voff)[_i]), (LAS unsigned*)(lds + (bufoff) + ldsw + _i * 8192), 16, 0, 0); } while (0)
; #define PG8_LDA(dst, b, h) do { _Pragma("unroll") for (int m = 0; m < 4; ++m) _Pragma("unroll") for (int k = 0; k < 2; ++k) dst[m][k] = *(const LAS bf16x8*)(lds + PG8_SA(b, h) + aoff + m * 2048 + k * 1024); } while (0)
; #define PG8_MMA(ai, bj, At, Bt) do { __builtin_amdgcn_s_setprio(1); _Pragma("unroll") for (int m = 0; m < 4; ++m) _Pragma("unroll") for (int n = 0; n < 2; ++n) _Pragma("unroll") for (int k = 0; k < 2; ++k) \
;         acc[ai][bj][m][n] = __builtin_amdgcn_mfma_f32_16x16x32_bf16(Bt[n][k], At[m][k], acc[ai][bj][m][n], 0, 0, 0); __builtin_amdgcn_s_setprio(0); } while (0)
; #define PG8_WAIT_V(n) asm volatile("s_waitcnt vmcnt(" #n ")" ::: "memory")
; #define PG8_WAIT_L(n) asm volatile("s_waitcnt lgkmcnt(" #n ")" ::: "memory")
; #define PG8_BAR __builtin_amdgcn_s_barrier()
; #define PG8_SCHED __builtin_amdgcn_sched_barrier(0)
; template <class Epi, bool SEG>
; __device__ __forceinline__ void gemm_phase(LAS unsigned char* lds, const Gemm g, const int G, const int cidx, const Epi& E) {
;     ...
;             PG8_LDA(At, 1, 1); PG8_STAGE(PG8_SB(1, 0), b3, voffB); PG8_STAGE(PG8_SB(1, 1), b3 + hstepB, voffB); PG8_STAGE(PG8_SA(1, 0), a3, voffA);
;             PG8_WAIT_V(8); PG8_WAIT_L(0); PG8_BAR; PG8_MMA(1, 0, At, B0); PG8_MMA(1, 1, At, B1); PG8_BAR; PG8_SCHED;
;         }
	s_setprio 0
	s_add_i32 s40, s55, s10
	v_lshl_add_u64 v[208:209], v[208:209], 0, s[28:29]
	s_mov_b32 m0, s40
	ds_read_b128 v[166:169], v247 offset:49152
	ds_read_b128 v[170:173], v247 offset:50176
	ds_read_b128 v[174:177], v247 offset:51200
	ds_read_b128 v[178:181], v247 offset:52224
	ds_read_b128 v[182:185], v247 offset:53248
	ds_read_b128 v[186:189], v247 offset:54272
	ds_read_b128 v[212:215], v247 offset:55296
	ds_read_b128 v[216:219], v247 offset:56320
	global_load_lds_dwordx4 v[208:209], off
	s_add_i32 m0, s40, 0x2000
	s_add_u32 s22, s22, 0x40080
	v_lshl_add_u64 v[208:209], v[220:221], 0, s[28:29]
	s_addc_u32 s23, s23, 0
	s_add_i32 s40, s56, s10
	global_load_lds_dwordx4 v[208:209], off
	v_lshl_add_u64 v[208:209], s[22:23], 0, v[0:1]
	s_mov_b32 m0, s40
	s_nop 0
	global_load_lds_dwordx4 v[208:209], off
	v_lshl_add_u64 v[208:209], s[22:23], 0, v[192:193]
	s_add_i32 m0, s40, 0x2000
	s_nop 0
	global_load_lds_dwordx4 v[208:209], off
	v_lshl_add_u64 v[208:209], v[222:223], 0, s[28:29]
	s_mov_b32 m0, s13
	s_nop 0
	global_load_lds_dwordx4 v[208:209], off
	v_lshl_add_u64 v[208:209], v[224:225], 0, s[28:29]
	s_mov_b32 m0, s8
	s_nop 0
	global_load_lds_dwordx4 v[208:209], off
	s_waitcnt vmcnt(8)
	s_waitcnt lgkmcnt(0)
	s_setprio 1
	s_barrier
	v_mfma_f32_16x16x32_bf16 v[98:101], v[102:105], v[166:169], v[98:101]
	v_mfma_f32_16x16x32_bf16 v[34:37], v[110:113], v[166:169], v[34:37]
	v_mfma_f32_16x16x32_bf16 v[94:97], v[102:105], v[174:177], v[94:97]
	v_mfma_f32_16x16x32_bf16 v[30:33], v[110:113], v[174:177], v[30:33]
	v_mfma_f32_16x16x32_bf16 v[82:85], v[102:105], v[182:185], v[82:85]
	v_mfma_f32_16x16x32_bf16 v[18:21], v[110:113], v[182:185], v[18:21]
	v_mfma_f32_16x16x32_bf16 v[74:77], v[102:105], v[212:215], v[74:77]
	v_mfma_f32_16x16x32_bf16 v[6:9], v[110:113], v[212:215], v[6:9]
	v_mfma_f32_16x16x32_bf16 v[98:101], v[106:109], v[170:173], v[98:101]
	v_mfma_f32_16x16x32_bf16 v[34:37], v[114:117], v[170:173], v[34:37]
	v_mfma_f32_16x16x32_bf16 v[94:97], v[106:109], v[178:181], v[94:97]
	v_mfma_f32_16x16x32_bf16 v[30:33], v[114:117], v[178:181], v[30:33]
	v_mfma_f32_16x16x32_bf16 v[82:85], v[106:109], v[186:189], v[82:85]
	v_mfma_f32_16x16x32_bf16 v[18:21], v[114:117], v[186:189], v[18:21]
	v_mfma_f32_16x16x32_bf16 v[74:77], v[106:109], v[216:219], v[74:77]
	v_mfma_f32_16x16x32_bf16 v[6:9], v[114:117], v[216:219], v[6:9]
	s_setprio 0
	s_setprio 1
	v_mfma_f32_16x16x32_bf16 v[90:93], v[118:121], v[166:169], v[90:93]
	v_mfma_f32_16x16x32_bf16 v[26:29], v[126:129], v[166:169], v[26:29]
	v_mfma_f32_16x16x32_bf16 v[86:89], v[118:121], v[174:177], v[86:89]
	v_mfma_f32_16x16x32_bf16 v[22:25], v[126:129], v[174:177], v[22:25]
	v_mfma_f32_16x16x32_bf16 v[78:81], v[118:121], v[182:185], v[78:81]
	v_mfma_f32_16x16x32_bf16 v[10:13], v[126:129], v[182:185], v[10:13]
	v_mfma_f32_16x16x32_bf16 v[70:73], v[118:121], v[212:215], v[70:73]
	v_mfma_f32_16x16x32_bf16 v[2:5], v[126:129], v[212:215], v[2:5]
	v_mfma_f32_16x16x32_bf16 v[90:93], v[122:125], v[170:173], v[90:93]
	v_mfma_f32_16x16x32_bf16 v[26:29], v[130:133], v[170:173], v[26:29]
	v_mfma_f32_16x16x32_bf16 v[86:89], v[122:125], v[178:181], v[86:89]
	v_mfma_f32_16x16x32_bf16 v[22:25], v[130:133], v[178:181], v[22:25]
	v_mfma_f32_16x16x32_bf16 v[78:81], v[122:125], v[186:189], v[78:81]
	v_mfma_f32_16x16x32_bf16 v[10:13], v[130:133], v[186:189], v[10:13]
	v_mfma_f32_16x16x32_bf16 v[70:73], v[122:125], v[216:219], v[70:73]
	v_mfma_f32_16x16x32_bf16 v[2:5], v[130:133], v[216:219], v[2:5]
	s_barrier
	s_setprio 0
	s_add_i32 s54, s54, 2
	s_add_u32 s6, s6, 0x100
	s_addc_u32 s7, s7, 0
	s_add_u32 s52, s52, 0x100
	s_addc_u32 s53, s53, 0

; #define PG8_STAGE(bufoff, gbase, voff) do { _Pragma("unroll") for (int _i = 0; _i < 2; ++_i) \
;         __builtin_amdgcn_global_load_lds((const unsigned*)((const char*)(gbase) + (voff)[_i]), (LAS unsigned*)(lds + (bufoff) + ldsw + _i * 8192), 16, 0, 0); } while (0)
; #define PG8_LDA(dst, b, h) do { _Pragma("unroll") for (int m = 0; m < 4; ++m) _Pragma("unroll") for (int k = 0; k < 2; ++k) dst[m][k] = *(const LAS bf16x8*)(lds + PG8_SA(b, h) + aoff + m * 2048 + k * 1024); } while (0)
; #define PG8_LDB(dst, b, h) do { _Pragma("unroll") for (int n = 0; n < 2; ++n) _Pragma("unroll") for (int k = 0; k < 2; ++k) dst[n][k] = *(const LAS bf16x8*)(lds + PG8_SB(b, h) + boff + n * 2048 + k * 1024); } while (0)
; #define PG8_MMA(ai, bj, At, Bt) do { __builtin_amdgcn_s_setprio(1); _Pragma("unroll") for (int m = 0; m < 4; ++m) _Pragma("unroll") for (int n = 0; n < 2; ++n) _Pragma("unroll") for (int k = 0; k < 2; ++k) \
;         acc[ai][bj][m][n] = __builtin_amdgcn_mfma_f32_16x16x32_bf16(Bt[n][k], At[m][k], acc[ai][bj][m][n], 0, 0, 0); __builtin_amdgcn_s_setprio(0); } while (0)
; #define PG8_BAR __builtin_amdgcn_s_barrier()
; template <class Epi, bool SEG>
; __device__ __forceinline__ void gemm_phase(LAS unsigned char* lds, const Gemm g, const int G, const int cidx, const Epi& E) {
;     ...
;         const bool has_next = S.next(ui + 1, nxt);
;         const char* nA = has_next ? (const char*)g.A + (long)nxt.pm * (long)tstepA + aoff0 : cA; const char* nB = has_next ? (const char*)g.Bt + (size_t)nxt.pn * tstepB : cB;
;         for (int t = 0; t < nt; t += 2) {
;             const bool last = (t == nt - 2);
;             const char* a1 = cA + (size_t)(t + 1) * kstep;
;             const char* a2 = last ? nA : cA + (size_t)(t + 2) * kstep; const char* b2 = last ? nB : cB + (size_t)(t + 2) * kstep;
;             const char* a3 = a2 + kstep; const char* b3 = b2 + kstep;
;             PG8_LDB(B0, 0, 0); PG8_LDB(B1, 0, 1); PG8_SCHED; PG8_LDA(At, 0, 0); PG8_STAGE(PG8_SA(1, 1), a1 + hstepA, voffA);
;             PG8_WAIT_V(8); PG8_WAIT_L(0); PG8_BAR; PG8_MMA(0, 0, At, B0); PG8_MMA(0, 1, At, B1); PG8_BAR; PG8_SCHED;
;             PG8_LDA(At, 0, 1); PG8_STAGE(PG8_SB(0, 0), b2, voffB); PG8_STAGE(PG8_SB(0, 1), b2 + hstepB, voffB); PG8_STAGE(PG8_SA(0, 0), a2, voffA);
;             PG8_WAIT_V(8); PG8_WAIT_L(0); PG8_BAR; PG8_MMA(1, 0, At, B0); PG8_MMA(1, 1, At, B1); PG8_BAR; PG8_SCHED;
.LBB0_957:
	s_add_u32 s52, s20, 0x100
	s_addc_u32 s53, s21, 0
	s_mov_b32 s54, -2
	s_waitcnt lgkmcnt(0)
	s_waitcnt vmcnt(0)
	s_add_u32 s20, s18, 0x100
	s_addc_u32 s21, s19, 0
	s_add_i32 s55, 0, 0x10000
	s_cmp_eq_u32 s54, 40
	s_cselect_b32 s47, s7, s21
	s_cselect_b32 s46, s6, s20
	s_cselect_b32 s23, s17, s53
	s_cselect_b32 s22, s16, s52
	s_add_i32 s56, 0, 0x14000
	v_add_u32_e32 v146, s55, v228
	v_add_u32_e32 v162, s56, v228
	ds_read_b128 v[130:133], v146
	ds_read_b128 v[138:141], v146 offset:1024
	ds_read_b128 v[142:145], v146 offset:2048
	ds_read_b128 v[146:149], v146 offset:3072
	ds_read_b128 v[150:153], v162
	ds_read_b128 v[154:157], v162 offset:1024
	ds_read_b128 v[158:161], v162 offset:2048
	ds_read_b128 v[162:165], v162 offset:3072
	v_lshl_add_u64 v[208:209], s[18:19], 0, v[198:199]
	s_add_i32 m0, s30, 0xc000
	ds_read_b128 v[166:169], v244
	ds_read_b128 v[170:173], v244 offset:1024
	ds_read_b128 v[174:177], v244 offset:2048
	ds_read_b128 v[178:181], v244 offset:3072
	ds_read_b128 v[182:185], v244 offset:4096
	ds_read_b128 v[186:189], v244 offset:5120
	ds_read_b128 v[190:193], v244 offset:6144
	ds_read_b128 v[212:215], v244 offset:7168
	global_load_lds_dwordx4 v[208:209], off
	v_lshl_add_u64 v[208:209], s[18:19], 0, v[200:201]
	s_add_i32 m0, s30, 0xe000
	s_nop 0
	global_load_lds_dwordx4 v[208:209], off
	s_waitcnt vmcnt(8)
	s_waitcnt lgkmcnt(0)
	s_setprio 1
	s_barrier
	v_mfma_f32_16x16x32_bf16 v[134:137], v[130:133], v[166:169], 0
	v_mfma_f32_16x16x32_bf16 v[126:129], v[142:145], v[166:169], 0
	v_mfma_f32_16x16x32_bf16 v[114:117], v[130:133], v[174:177], 0
	v_mfma_f32_16x16x32_bf16 v[110:113], v[142:145], v[174:177], 0
	v_mfma_f32_16x16x32_bf16 v[98:101], v[130:133], v[182:185], 0
	v_mfma_f32_16x16x32_bf16 v[94:97], v[142:145], v[182:185], 0
	v_mfma_f32_16x16x32_bf16 v[82:85], v[130:133], v[190:193], 0
	v_mfma_f32_16x16x32_bf16 v[78:81], v[142:145], v[190:193], 0
	v_mfma_f32_16x16x32_bf16 v[134:137], v[138:141], v[170:173], v[134:137]
	v_mfma_f32_16x16x32_bf16 v[126:129], v[146:149], v[170:173], v[126:129]
	v_mfma_f32_16x16x32_bf16 v[114:117], v[138:141], v[178:181], v[114:117]
	v_mfma_f32_16x16x32_bf16 v[110:113], v[146:149], v[178:181], v[110:113]
	v_mfma_f32_16x16x32_bf16 v[98:101], v[138:141], v[186:189], v[98:101]
	v_mfma_f32_16x16x32_bf16 v[94:97], v[146:149], v[186:189], v[94:97]
	v_mfma_f32_16x16x32_bf16 v[82:85], v[138:141], v[212:215], v[82:85]
	v_mfma_f32_16x16x32_bf16 v[78:81], v[146:149], v[212:215], v[78:81]
	s_setprio 0
	s_setprio 1
	v_mfma_f32_16x16x32_bf16 v[122:125], v[150:153], v[166:169], 0
	v_mfma_f32_16x16x32_bf16 v[118:121], v[158:161], v[166:169], 0
	v_mfma_f32_16x16x32_bf16 v[106:109], v[150:153], v[174:177], 0
	v_mfma_f32_16x16x32_bf16 v[102:105], v[158:161], v[174:177], 0
	v_mfma_f32_16x16x32_bf16 v[90:93], v[150:153], v[182:185], 0
	v_mfma_f32_16x16x32_bf16 v[86:89], v[158:161], v[182:185], 0
	v_mfma_f32_16x16x32_bf16 v[74:77], v[150:153], v[190:193], 0
	v_mfma_f32_16x16x32_bf16 v[70:73], v[158:161], v[190:193], 0
	v_mfma_f32_16x16x32_bf16 v[122:125], v[154:157], v[170:173], v[122:125]
	v_mfma_f32_16x16x32_bf16 v[118:121], v[162:165], v[170:173], v[118:121]
	v_mfma_f32_16x16x32_bf16 v[106:109], v[154:157], v[178:181], v[106:109]
	v_mfma_f32_16x16x32_bf16 v[102:105], v[162:165], v[178:181], v[102:105]
	v_mfma_f32_16x16x32_bf16 v[90:93], v[154:157], v[186:189], v[90:93]
	v_mfma_f32_16x16x32_bf16 v[86:89], v[162:165], v[186:189], v[86:89]
	v_mfma_f32_16x16x32_bf16 v[74:77], v[154:157], v[212:215], v[74:77]
	v_mfma_f32_16x16x32_bf16 v[70:73], v[162:165], v[212:215], v[70:73]
	s_barrier
	s_setprio 0
	s_add_i32 s18, s55, s9
	v_lshl_add_u64 v[208:209], s[22:23], 0, v[0:1]
	s_mov_b32 m0, s18
	ds_read_b128 v[166:169], v244 offset:16384
	ds_read_b128 v[170:173], v244 offset:17408
	ds_read_b128 v[174:177], v244 offset:18432
	ds_read_b128 v[178:181], v244 offset:19456
	ds_read_b128 v[182:185], v244 offset:20480
	ds_read_b128 v[186:189], v244 offset:21504
	ds_read_b128 v[190:193], v244 offset:22528
	ds_read_b128 v[212:215], v244 offset:23552
	global_load_lds_dwordx4 v[208:209], off
	s_add_i32 m0, s18, 0x2000
	s_add_u32 s18, s22, 0xb0000
	v_lshl_add_u64 v[216:217], s[22:23], 0, v[14:15]
	s_addc_u32 s19, s23, 0
	s_add_i32 s55, s56, s9
	global_load_lds_dwordx4 v[216:217], off
	v_lshl_add_u64 v[218:219], s[18:19], 0, v[0:1]
	s_mov_b32 m0, s55
	v_lshl_add_u64 v[220:221], s[46:47], 0, v[194:195]
	global_load_lds_dwordx4 v[218:219], off
	v_lshl_add_u64 v[218:219], s[18:19], 0, v[14:15]
	s_add_i32 m0, s55, 0x2000
	s_nop 0
	global_load_lds_dwordx4 v[218:219], off
	v_lshl_add_u64 v[218:219], s[46:47], 0, v[196:197]
	s_mov_b32 m0, s30
	s_nop 0
	global_load_lds_dwordx4 v[218:219], off
	s_mov_b32 m0, s31
	s_nop 0
	global_load_lds_dwordx4 v[220:221], off
	s_waitcnt vmcnt(8)
	s_waitcnt lgkmcnt(0)
	s_setprio 1
	s_barrier
; #define PG8_STAGE(bufoff, gbase, voff) do { _Pragma("unroll") for (int _i = 0; _i < 2; ++_i) \
;         __builtin_amdgcn_global_load_lds((const unsigned*)((const char*)(gbase) + (voff)[_i]), (LAS unsigned*)(lds + (bufoff) + ldsw + _i * 8192), 16, 0, 0); } while (0)
; #define PG8_LDA(dst, b, h) do { _Pragma("unroll") for (int m = 0; m < 4; ++m) _Pragma("unroll") for (int k = 0; k < 2; ++k) dst[m][k] = *(const LAS bf16x8*)(lds + PG8_SA(b, h) + aoff + m * 2048 + k * 1024); } while (0)
; #define PG8_LDB(dst, b, h) do { _Pragma("unroll") for (int n = 0; n < 2; ++n) _Pragma("unroll") for (int k = 0; k < 2; ++k) dst[n][k] = *(const LAS bf16x8*)(lds + PG8_SB(b, h) + boff + n * 2048 + k * 1024); } while (0)
; #define PG8_MMA(ai, bj, At, Bt) do { __builtin_amdgcn_s_setprio(1); _Pragma("unroll") for (int m = 0; m < 4; ++m) _Pragma("unroll") for (int n = 0; n < 2; ++n) _Pragma("unroll") for (int k = 0; k < 2; ++k) \
;         acc[ai][bj][m][n] = __builtin_amdgcn_mfma_f32_16x16x32_bf16(Bt[n][k], At[m][k], acc[ai][bj][m][n], 0, 0, 0); __builtin_amdgcn_s_setprio(0); } while (0)
; #define PG8_WAIT_V(n) asm volatile("s_waitcnt vmcnt(" #n ")" ::: "memory")
; #define PG8_WAIT_L(n) asm volatile("s_waitcnt lgkmcnt(" #n ")" ::: "memory")
; #define PG8_BAR __builtin_amdgcn_s_barrier()
; #define PG8_SCHED __builtin_amdgcn_sched_barrier(0)
; template <class Epi, bool SEG>
; __device__ __forceinline__ void gemm_phase(LAS unsigned char* lds, const Gemm g, const int G, const int cidx, const Epi& E) {
;     ...
;             PG8_WAIT_V(8); PG8_WAIT_L(0); PG8_BAR; PG8_MMA(1, 0, At, B0); PG8_MMA(1, 1, At, B1); PG8_BAR; PG8_SCHED;
;             PG8_LDB(B0, 1, 0); PG8_LDB(B1, 1, 1); PG8_SCHED; PG8_LDA(At, 1, 0); PG8_STAGE(PG8_SA(0, 1), a2 + hstepA, voffA);
;             PG8_WAIT_V(8); PG8_WAIT_L(0); PG8_BAR; PG8_MMA(0, 0, At, B0); PG8_MMA(0, 1, At, B1); PG8_BAR; PG8_SCHED;
;             PG8_LDA(At, 1, 1); PG8_STAGE(PG8_SB(1, 0), b3, voffB); PG8_STAGE(PG8_SB(1, 1), b3 + hstepB, voffB); PG8_STAGE(PG8_SA(1, 0), a3, voffA);
	v_mfma_f32_16x16x32_bf16 v[66:69], v[130:133], v[166:169], 0
	v_mfma_f32_16x16x32_bf16 v[62:65], v[142:145], v[166:169], 0
	v_mfma_f32_16x16x32_bf16 v[50:53], v[130:133], v[174:177], 0
	v_mfma_f32_16x16x32_bf16 v[46:49], v[142:145], v[174:177], 0
	v_mfma_f32_16x16x32_bf16 v[34:37], v[130:133], v[182:185], 0
	v_mfma_f32_16x16x32_bf16 v[30:33], v[142:145], v[182:185], 0
	v_mfma_f32_16x16x32_bf16 v[18:21], v[130:133], v[190:193], 0
	v_mfma_f32_16x16x32_bf16 v[10:13], v[142:145], v[190:193], 0
	v_mfma_f32_16x16x32_bf16 v[66:69], v[138:141], v[170:173], v[66:69]
	v_mfma_f32_16x16x32_bf16 v[62:65], v[146:149], v[170:173], v[62:65]
	v_mfma_f32_16x16x32_bf16 v[50:53], v[138:141], v[178:181], v[50:53]
	v_mfma_f32_16x16x32_bf16 v[46:49], v[146:149], v[178:181], v[46:49]
	v_mfma_f32_16x16x32_bf16 v[34:37], v[138:141], v[186:189], v[34:37]
	v_mfma_f32_16x16x32_bf16 v[30:33], v[146:149], v[186:189], v[30:33]
	v_mfma_f32_16x16x32_bf16 v[18:21], v[138:141], v[212:215], v[18:21]
	v_mfma_f32_16x16x32_bf16 v[10:13], v[146:149], v[212:215], v[10:13]
	s_setprio 0
	s_setprio 1
	v_mfma_f32_16x16x32_bf16 v[58:61], v[150:153], v[166:169], 0
	v_mfma_f32_16x16x32_bf16 v[54:57], v[158:161], v[166:169], 0
	v_mfma_f32_16x16x32_bf16 v[42:45], v[150:153], v[174:177], 0
	v_mfma_f32_16x16x32_bf16 v[38:41], v[158:161], v[174:177], 0
	v_mfma_f32_16x16x32_bf16 v[26:29], v[150:153], v[182:185], 0
	v_mfma_f32_16x16x32_bf16 v[22:25], v[158:161], v[182:185], 0
	v_mfma_f32_16x16x32_bf16 v[6:9], v[150:153], v[190:193], 0
	v_mfma_f32_16x16x32_bf16 v[2:5], v[158:161], v[190:193], 0
	v_mfma_f32_16x16x32_bf16 v[58:61], v[154:157], v[170:173], v[58:61]
	v_mfma_f32_16x16x32_bf16 v[54:57], v[162:165], v[170:173], v[54:57]
	v_mfma_f32_16x16x32_bf16 v[42:45], v[154:157], v[178:181], v[42:45]
	v_mfma_f32_16x16x32_bf16 v[38:41], v[162:165], v[178:181], v[38:41]
	v_mfma_f32_16x16x32_bf16 v[26:29], v[154:157], v[186:189], v[26:29]
	v_mfma_f32_16x16x32_bf16 v[22:25], v[162:165], v[186:189], v[22:25]
	v_mfma_f32_16x16x32_bf16 v[6:9], v[154:157], v[212:215], v[6:9]
	v_mfma_f32_16x16x32_bf16 v[2:5], v[162:165], v[212:215], v[2:5]
	s_barrier
	s_setprio 0
	s_add_i32 s55, 0, 0x18000
	s_add_i32 s56, 0, 0x1c000
	v_add_u32_e32 v146, s55, v228
	v_add_u32_e32 v162, s56, v228
	ds_read_b128 v[130:133], v146
	ds_read_b128 v[138:141], v146 offset:1024
	ds_read_b128 v[142:145], v146 offset:2048
	ds_read_b128 v[146:149], v146 offset:3072
	ds_read_b128 v[150:153], v162
	ds_read_b128 v[154:157], v162 offset:1024
	ds_read_b128 v[158:161], v162 offset:2048
	ds_read_b128 v[162:165], v162 offset:3072
	s_add_u32 s18, s46, 0xb0000
	s_addc_u32 s19, s47, 0
	s_mov_b32 m0, s36
	v_lshl_add_u64 v[222:223], s[18:19], 0, v[196:197]
	ds_read_b128 v[166:169], v244 offset:32768
	ds_read_b128 v[170:173], v244 offset:33792
	ds_read_b128 v[174:177], v244 offset:34816
	ds_read_b128 v[178:181], v244 offset:35840
	ds_read_b128 v[182:185], v244 offset:36864
	ds_read_b128 v[186:189], v244 offset:37888
	ds_read_b128 v[190:193], v244 offset:38912
	ds_read_b128 v[212:215], v244 offset:39936
	global_load_lds_dwordx4 v[222:223], off
	v_lshl_add_u64 v[222:223], s[18:19], 0, v[194:195]
	s_mov_b32 m0, s38
	s_nop 0
	global_load_lds_dwordx4 v[222:223], off
	s_waitcnt vmcnt(8)
	s_waitcnt lgkmcnt(0)
	s_setprio 1
	s_barrier
	v_mfma_f32_16x16x32_bf16 v[134:137], v[130:133], v[166:169], v[134:137]
	v_mfma_f32_16x16x32_bf16 v[126:129], v[142:145], v[166:169], v[126:129]
	v_mfma_f32_16x16x32_bf16 v[114:117], v[130:133], v[174:177], v[114:117]
	v_mfma_f32_16x16x32_bf16 v[110:113], v[142:145], v[174:177], v[110:113]
	v_mfma_f32_16x16x32_bf16 v[98:101], v[130:133], v[182:185], v[98:101]
	v_mfma_f32_16x16x32_bf16 v[94:97], v[142:145], v[182:185], v[94:97]
	v_mfma_f32_16x16x32_bf16 v[82:85], v[130:133], v[190:193], v[82:85]
	v_mfma_f32_16x16x32_bf16 v[78:81], v[142:145], v[190:193], v[78:81]
	v_mfma_f32_16x16x32_bf16 v[134:137], v[138:141], v[170:173], v[134:137]
	v_mfma_f32_16x16x32_bf16 v[126:129], v[146:149], v[170:173], v[126:129]
	v_mfma_f32_16x16x32_bf16 v[114:117], v[138:141], v[178:181], v[114:117]
	v_mfma_f32_16x16x32_bf16 v[110:113], v[146:149], v[178:181], v[110:113]
	v_mfma_f32_16x16x32_bf16 v[98:101], v[138:141], v[186:189], v[98:101]
	v_mfma_f32_16x16x32_bf16 v[94:97], v[146:149], v[186:189], v[94:97]
	v_mfma_f32_16x16x32_bf16 v[82:85], v[138:141], v[212:215], v[82:85]
	v_mfma_f32_16x16x32_bf16 v[78:81], v[146:149], v[212:215], v[78:81]
	s_setprio 0
	s_setprio 1
	v_mfma_f32_16x16x32_bf16 v[122:125], v[150:153], v[166:169], v[122:125]
	v_mfma_f32_16x16x32_bf16 v[118:121], v[158:161], v[166:169], v[118:121]
	v_mfma_f32_16x16x32_bf16 v[106:109], v[150:153], v[174:177], v[106:109]
	v_mfma_f32_16x16x32_bf16 v[102:105], v[158:161], v[174:177], v[102:105]
	v_mfma_f32_16x16x32_bf16 v[90:93], v[150:153], v[182:185], v[90:93]
	v_mfma_f32_16x16x32_bf16 v[86:89], v[158:161], v[182:185], v[86:89]
	v_mfma_f32_16x16x32_bf16 v[74:77], v[150:153], v[190:193], v[74:77]
	v_mfma_f32_16x16x32_bf16 v[70:73], v[158:161], v[190:193], v[70:73]
	v_mfma_f32_16x16x32_bf16 v[122:125], v[154:157], v[170:173], v[122:125]
	v_mfma_f32_16x16x32_bf16 v[118:121], v[162:165], v[170:173], v[118:121]
	v_mfma_f32_16x16x32_bf16 v[106:109], v[154:157], v[178:181], v[106:109]
	v_mfma_f32_16x16x32_bf16 v[102:105], v[162:165], v[178:181], v[102:105]
	v_mfma_f32_16x16x32_bf16 v[90:93], v[154:157], v[186:189], v[90:93]
	v_mfma_f32_16x16x32_bf16 v[86:89], v[162:165], v[186:189], v[86:89]
	v_mfma_f32_16x16x32_bf16 v[74:77], v[154:157], v[212:215], v[74:77]
	v_mfma_f32_16x16x32_bf16 v[70:73], v[162:165], v[212:215], v[70:73]
	s_barrier
; #define PG8_STAGE(bufoff, gbase, voff) do { _Pragma("unroll") for (int _i = 0; _i < 2; ++_i) \
;         __builtin_amdgcn_global_load_lds((const unsigned*)((const char*)(gbase) + (voff)[_i]), (LAS unsigned*)(lds + (bufoff) + ldsw + _i * 8192), 16, 0, 0); } while (0)
; #define PG8_LDA(dst, b, h) do { _Pragma("unroll") for (int m = 0; m < 4; ++m) _Pragma("unroll") for (int k = 0; k < 2; ++k) dst[m][k] = *(const LAS bf16x8*)(lds + PG8_SA(b, h) + aoff + m * 2048 + k * 1024); } while (0)
; #define PG8_MMA(ai, bj, At, Bt) do { __builtin_amdgcn_s_setprio(1); _Pragma("unroll") for (int m = 0; m < 4; ++m) _Pragma("unroll") for (int n = 0; n < 2; ++n) _Pragma("unroll") for (int k = 0; k < 2; ++k) \
;         acc[ai][bj][m][n] = __builtin_amdgcn_mfma_f32_16x16x32_bf16(Bt[n][k], At[m][k], acc[ai][bj][m][n], 0, 0, 0); __builtin_amdgcn_s_setprio(0); } while (0)
; #define PG8_WAIT_V(n) asm volatile("s_waitcnt vmcnt(" #n ")" ::: "memory")
; #define PG8_WAIT_L(n) asm volatile("s_waitcnt lgkmcnt(" #n ")" ::: "memory")
; #define PG8_BAR __builtin_amdgcn_s_barrier()
; #define PG8_SCHED __builtin_amdgcn_sched_barrier(0)
; template <class Epi, bool SEG>
; __device__ __forceinline__ void gemm_phase(LAS unsigned char* lds, const Gemm g, const int G, const int cidx, const Epi& E) {
;     ...
;             PG8_LDA(At, 1, 1); PG8_STAGE(PG8_SB(1, 0), b3, voffB); PG8_STAGE(PG8_SB(1, 1), b3 + hstepB, voffB); PG8_STAGE(PG8_SA(1, 0), a3, voffA);
;             PG8_WAIT_V(8); PG8_WAIT_L(0); PG8_BAR; PG8_MMA(1, 0, At, B0); PG8_MMA(1, 1, At, B1); PG8_BAR; PG8_SCHED;
;         }
	s_setprio 0
	s_add_i32 s18, s55, s9
	v_lshl_add_u64 v[208:209], v[208:209], 0, s[28:29]
	s_mov_b32 m0, s18
	ds_read_b128 v[166:169], v244 offset:49152
	ds_read_b128 v[170:173], v244 offset:50176
	ds_read_b128 v[174:177], v244 offset:51200
	ds_read_b128 v[178:181], v244 offset:52224
	ds_read_b128 v[182:185], v244 offset:53248
	ds_read_b128 v[186:189], v244 offset:54272
	ds_read_b128 v[190:193], v244 offset:55296
	ds_read_b128 v[212:215], v244 offset:56320
	global_load_lds_dwordx4 v[208:209], off
	s_add_i32 m0, s18, 0x2000
	s_add_u32 s18, s22, 0xb0080
	v_lshl_add_u64 v[208:209], v[216:217], 0, s[28:29]
	s_addc_u32 s19, s23, 0
	s_add_i32 s22, s56, s9
	global_load_lds_dwordx4 v[208:209], off
	v_lshl_add_u64 v[208:209], s[18:19], 0, v[0:1]
	s_mov_b32 m0, s22
	s_nop 0
	global_load_lds_dwordx4 v[208:209], off
	v_lshl_add_u64 v[208:209], s[18:19], 0, v[14:15]
	s_add_i32 m0, s22, 0x2000
	s_nop 0
	global_load_lds_dwordx4 v[208:209], off
	v_lshl_add_u64 v[208:209], v[218:219], 0, s[28:29]
	s_mov_b32 m0, s39
	s_nop 0
	global_load_lds_dwordx4 v[208:209], off
	v_lshl_add_u64 v[208:209], v[220:221], 0, s[28:29]
	s_mov_b32 m0, s48
	s_nop 0
	global_load_lds_dwordx4 v[208:209], off
	s_waitcnt vmcnt(8)
	s_waitcnt lgkmcnt(0)
	s_setprio 1
	s_barrier
	v_mfma_f32_16x16x32_bf16 v[66:69], v[130:133], v[166:169], v[66:69]
	v_mfma_f32_16x16x32_bf16 v[62:65], v[142:145], v[166:169], v[62:65]
	v_mfma_f32_16x16x32_bf16 v[50:53], v[130:133], v[174:177], v[50:53]
	v_mfma_f32_16x16x32_bf16 v[46:49], v[142:145], v[174:177], v[46:49]
	v_mfma_f32_16x16x32_bf16 v[34:37], v[130:133], v[182:185], v[34:37]
	v_mfma_f32_16x16x32_bf16 v[30:33], v[142:145], v[182:185], v[30:33]
	v_mfma_f32_16x16x32_bf16 v[18:21], v[130:133], v[190:193], v[18:21]
	v_mfma_f32_16x16x32_bf16 v[10:13], v[142:145], v[190:193], v[10:13]
	v_mfma_f32_16x16x32_bf16 v[66:69], v[138:141], v[170:173], v[66:69]
	v_mfma_f32_16x16x32_bf16 v[62:65], v[146:149], v[170:173], v[62:65]
	v_mfma_f32_16x16x32_bf16 v[50:53], v[138:141], v[178:181], v[50:53]
	v_mfma_f32_16x16x32_bf16 v[46:49], v[146:149], v[178:181], v[46:49]
	v_mfma_f32_16x16x32_bf16 v[34:37], v[138:141], v[186:189], v[34:37]
	v_mfma_f32_16x16x32_bf16 v[30:33], v[146:149], v[186:189], v[30:33]
	v_mfma_f32_16x16x32_bf16 v[18:21], v[138:141], v[212:215], v[18:21]
	v_mfma_f32_16x16x32_bf16 v[10:13], v[146:149], v[212:215], v[10:13]
	s_setprio 0
	s_setprio 1
	v_mfma_f32_16x16x32_bf16 v[58:61], v[150:153], v[166:169], v[58:61]
	v_mfma_f32_16x16x32_bf16 v[54:57], v[158:161], v[166:169], v[54:57]
	v_mfma_f32_16x16x32_bf16 v[42:45], v[150:153], v[174:177], v[42:45]
	v_mfma_f32_16x16x32_bf16 v[38:41], v[158:161], v[174:177], v[38:41]
	v_mfma_f32_16x16x32_bf16 v[26:29], v[150:153], v[182:185], v[26:29]
	v_mfma_f32_16x16x32_bf16 v[22:25], v[158:161], v[182:185], v[22:25]
	v_mfma_f32_16x16x32_bf16 v[6:9], v[150:153], v[190:193], v[6:9]
	v_mfma_f32_16x16x32_bf16 v[2:5], v[158:161], v[190:193], v[2:5]
	v_mfma_f32_16x16x32_bf16 v[58:61], v[154:157], v[170:173], v[58:61]
	v_mfma_f32_16x16x32_bf16 v[54:57], v[162:165], v[170:173], v[54:57]
	v_mfma_f32_16x16x32_bf16 v[42:45], v[154:157], v[178:181], v[42:45]
	v_mfma_f32_16x16x32_bf16 v[38:41], v[162:165], v[178:181], v[38:41]
	v_mfma_f32_16x16x32_bf16 v[26:29], v[154:157], v[186:189], v[26:29]
	v_mfma_f32_16x16x32_bf16 v[22:25], v[162:165], v[186:189], v[22:25]
	v_mfma_f32_16x16x32_bf16 v[6:9], v[154:157], v[212:215], v[6:9]
	v_mfma_f32_16x16x32_bf16 v[2:5], v[162:165], v[212:215], v[2:5]
	s_barrier
	s_setprio 0
	s_add_i32 s54, s54, 2
	s_add_u32 s52, s52, 0x100
	s_addc_u32 s53, s53, 0
	s_mov_b64 s[18:19], s[20:21]
